# GEMM K loops: residual GEMMs' LDS-DMA addresses in SGPR-base form too, and the B-fragment ds_read bases come from one loop-invariant register with immediate offsets: no VALU instruction left in the th
# baseline (speedup 1.0000x reference)
; #define PG8_STAGE(bufoff, gbase, voff) do { _Pragma("unroll") for (int _i = 0; _i < 2; ++_i) \
;         __builtin_amdgcn_global_load_lds((const unsigned*)((const char*)(gbase) + (voff)[_i]), (PG8_LAS unsigned*)(lds + (bufoff) + ldsw + _i * 8192), 16, 0, 0); } while (0)
; #define PG8_LDA(dst, b, h) do { _Pragma("unroll") for (int m = 0; m < 4; ++m) _Pragma("unroll") for (int k = 0; k < 2; ++k) dst[m][k] = *(const PG8_LAS bf16x8*)(lds + PG8_SA(b, h) + aoff + m * 2048 + k * 1024); } while (0)
; #define PG8_LDB(dst, b, h) do { _Pragma("unroll") for (int n = 0; n < 2; ++n) _Pragma("unroll") for (int k = 0; k < 2; ++k) dst[n][k] = *(const PG8_LAS bf16x8*)(lds + PG8_SB(b, h) + boff + n * 2048 + k * 1024); } while (0)
; #define PG8_WAIT_V(n) asm volatile("s_waitcnt vmcnt(" #n ")" ::: "memory")
; #define PG8_WAIT_L(n) asm volatile("s_waitcnt lgkmcnt(" #n ")" ::: "memory")
; #define PG8_BAR __builtin_amdgcn_s_barrier()
; #define PG8_SCHED __builtin_amdgcn_sched_barrier(0)
; template <class Epi, class Sched, bool ALIGN_EPI = false, bool SP2 = false>
; __device__ __forceinline__ void gemm_phase(PG8_LAS unsigned char* lds, const Gemm g, const Sched& S, const Epi& E) {
;     ...
;     f32x4 acc[2][2][4][2];
; #pragma unroll
;     for (int a = 0; a < 2; ++a)
; #pragma unroll
;         for (int b = 0; b < 2; ++b)
; #pragma unroll
;             for (int m = 0; m < 4; ++m)
; #pragma unroll
;                 for (int n = 0; n < 2; ++n) acc[a][b][m][n] = (f32x4){0.f, 0.f, 0.f, 0.f};
;     ...
;         const bool has_next = S.next(ui + 1, nxt);
;         const char* nA = has_next ? (const char*)g.A + (size_t)nxt.pm * tstep : cA; const char* nB = has_next ? (const char*)g.Bt + (size_t)nxt.pn * tstep : cB;
;         for (int t = 0; t < nt; t += 2) {
;             const bool last = (t == nt - 2);
;             const char* a1 = cA + (size_t)(t + 1) * kstep;
;             const char* a2 = last ? nA : cA + (size_t)(t + 2) * kstep; const char* b2 = last ? nB : cB + (size_t)(t + 2) * kstep;
;             const char* a3 = a2 + kstep; const char* b3 = b2 + kstep;
;             if (last && has_next) S.a_ready(nxt);
;             if constexpr (SP2) {
;             PG8_LDB(B0, 0, 0); PG8_LDB(B1, 0, 1); PG8_SCHED; PG8_LDA(At, 0, 0); PG8_STAGE(PG8_SA(1, 1), a1 + hstep, voffA);
;             PG8_WAIT_V(8); PG8_WAIT_L(0); PG8_BAR; PG8_MMA(0, 0, At, B0); PG8_MMA(0, 1, At, B1); PG8_BAR; PG8_SCHED;
.Lstg_done:
	s_ashr_i32 s27, s26, 31
	s_lshl_b64 s[12:13], s[26:27], 20
	s_add_u32 s94, s18, s12
	s_addc_u32 s95, s19, s13
	s_and_b64 s[12:13], s[46:47], exec
	s_cselect_b32 s27, s95, s69
	s_cselect_b32 s86, s94, s68
	s_ashr_i32 s17, s16, 31
	s_lshl_b64 s[12:13], s[16:17], 20
	v_readlane_b32 s14, v254, 38
	v_readlane_b32 s15, v254, 39
	s_add_u32 s14, s14, s12
	s_addc_u32 s15, s15, s13
	s_and_b64 s[12:13], s[46:47], exec
	s_cselect_b32 s17, s15, s11
	s_cselect_b32 s88, s14, s10
	s_add_u32 vcc_lo, s68, 0x80080
	s_addc_u32 vcc_hi, s69, 0
	s_add_u32 s21, s10, 0x100
	v_mov_b32_e32 v6, 0
	s_addc_u32 s12, s11, 0
	s_mov_b32 s13, -2
	v_mov_b32_e32 v7, v6
	v_mov_b32_e32 v8, v6
	v_mov_b32_e32 v9, v6
	v_mov_b32_e32 v70, v6
	v_mov_b32_e32 v71, v6
	v_mov_b32_e32 v72, v6
	v_mov_b32_e32 v73, v6
	v_mov_b32_e32 v14, v6
	v_mov_b32_e32 v15, v6
	v_mov_b32_e32 v16, v6
	v_mov_b32_e32 v17, v6
	v_mov_b32_e32 v78, v6
	v_mov_b32_e32 v79, v6
	v_mov_b32_e32 v80, v6
	v_mov_b32_e32 v81, v6
	v_mov_b32_e32 v22, v6
	v_mov_b32_e32 v23, v6
	v_mov_b32_e32 v24, v6
	v_mov_b32_e32 v25, v6
	v_mov_b32_e32 v86, v6
	v_mov_b32_e32 v87, v6
	v_mov_b32_e32 v88, v6
	v_mov_b32_e32 v89, v6
	v_mov_b32_e32 v26, v6
	v_mov_b32_e32 v27, v6
	v_mov_b32_e32 v28, v6
	v_mov_b32_e32 v29, v6
	v_mov_b32_e32 v90, v6
	v_mov_b32_e32 v91, v6
	v_mov_b32_e32 v92, v6
	v_mov_b32_e32 v93, v6
	v_mov_b32_e32 v2, v6
	v_mov_b32_e32 v3, v6
	v_mov_b32_e32 v4, v6
	v_mov_b32_e32 v5, v6
	v_mov_b32_e32 v66, v6
	v_mov_b32_e32 v67, v6
	v_mov_b32_e32 v68, v6
	v_mov_b32_e32 v69, v6
	v_mov_b32_e32 v10, v6
	v_mov_b32_e32 v11, v6
	v_mov_b32_e32 v12, v6
	v_mov_b32_e32 v13, v6
	v_mov_b32_e32 v74, v6
	v_mov_b32_e32 v75, v6
	v_mov_b32_e32 v76, v6
	v_mov_b32_e32 v77, v6
	v_mov_b32_e32 v18, v6
	v_mov_b32_e32 v19, v6
	v_mov_b32_e32 v20, v6
	v_mov_b32_e32 v21, v6
	v_mov_b32_e32 v82, v6
	v_mov_b32_e32 v83, v6
	v_mov_b32_e32 v84, v6
	v_mov_b32_e32 v85, v6
	v_mov_b32_e32 v30, v6
	v_mov_b32_e32 v31, v6
	v_mov_b32_e32 v32, v6
	v_mov_b32_e32 v33, v6
	v_mov_b32_e32 v94, v6
	v_mov_b32_e32 v95, v6
	v_mov_b32_e32 v96, v6
	v_mov_b32_e32 v97, v6
	v_mov_b32_e32 v38, v6
	v_mov_b32_e32 v39, v6
	v_mov_b32_e32 v40, v6
	v_mov_b32_e32 v41, v6
	v_mov_b32_e32 v102, v6
	v_mov_b32_e32 v103, v6
	v_mov_b32_e32 v104, v6
	v_mov_b32_e32 v105, v6
	v_mov_b32_e32 v46, v6
	v_mov_b32_e32 v47, v6
	v_mov_b32_e32 v48, v6
	v_mov_b32_e32 v49, v6
	v_mov_b32_e32 v110, v6
	v_mov_b32_e32 v111, v6
	v_mov_b32_e32 v112, v6
	v_mov_b32_e32 v113, v6
	v_mov_b32_e32 v54, v6
	v_mov_b32_e32 v55, v6
	v_mov_b32_e32 v56, v6
	v_mov_b32_e32 v57, v6
	v_mov_b32_e32 v126, v6
	v_mov_b32_e32 v127, v6
	v_mov_b32_e32 v128, v6
	v_mov_b32_e32 v129, v6
	v_mov_b32_e32 v58, v6
	v_mov_b32_e32 v59, v6
	v_mov_b32_e32 v60, v6
	v_mov_b32_e32 v61, v6
	v_mov_b32_e32 v134, v6
	v_mov_b32_e32 v135, v6
	v_mov_b32_e32 v136, v6
	v_mov_b32_e32 v137, v6
	v_mov_b32_e32 v34, v6
	v_mov_b32_e32 v35, v6
	v_mov_b32_e32 v36, v6
	v_mov_b32_e32 v37, v6
	v_mov_b32_e32 v98, v6
	v_mov_b32_e32 v99, v6
	v_mov_b32_e32 v100, v6
	v_mov_b32_e32 v101, v6
	v_mov_b32_e32 v42, v6
	v_mov_b32_e32 v43, v6
	v_mov_b32_e32 v44, v6
	v_mov_b32_e32 v45, v6
	v_mov_b32_e32 v106, v6
	v_mov_b32_e32 v107, v6
	v_mov_b32_e32 v108, v6
	v_mov_b32_e32 v109, v6
	v_mov_b32_e32 v50, v6
	v_mov_b32_e32 v51, v6
	v_mov_b32_e32 v52, v6
	v_mov_b32_e32 v53, v6
	v_mov_b32_e32 v122, v6
	v_mov_b32_e32 v123, v6
	v_mov_b32_e32 v124, v6
	v_mov_b32_e32 v125, v6
	v_mov_b32_e32 v62, v6
	v_mov_b32_e32 v63, v6
	v_mov_b32_e32 v64, v6
	v_mov_b32_e32 v65, v6
	v_mov_b32_e32 v142, v6
	v_mov_b32_e32 v143, v6
	v_mov_b32_e32 v144, v6
	v_mov_b32_e32 v145, v6
	v_add_u32_e32 v218, 0x10000, v194
.LBB0_38:
	s_add_u32 s10, vcc_lo, 0xfff80080
	s_addc_u32 s11, vcc_hi, -1
	s_add_i32 s84, 0, 0x10000
	s_cmp_eq_u32 s13, 28
	s_cselect_b32 s69, s27, s11
	s_cselect_b32 s68, s86, s10
	s_cselect_b32 s11, s17, s12
	s_cselect_b32 s10, s88, s21
	s_add_i32 s93, 0, 0x14000
	ds_read_b128 v[114:117], v218
	ds_read_b128 v[118:121], v218 offset:1024
	ds_read_b128 v[130:133], v218 offset:2048
	ds_read_b128 v[138:141], v218 offset:3072
	ds_read_b128 v[146:149], v218 offset:16384
	ds_read_b128 v[156:159], v218 offset:17408
	ds_read_b128 v[160:163], v218 offset:18432
	ds_read_b128 v[164:167], v218 offset:19456
	s_add_i32 m0, s2, 0xc000
	ds_read_b128 v[168:171], v199
	ds_read_b128 v[172:175], v199 offset:1024
	ds_read_b128 v[176:179], v199 offset:2048
	ds_read_b128 v[180:183], v199 offset:3072
	ds_read_b128 v[184:187], v199 offset:4096
	ds_read_b128 v[188:191], v199 offset:5120
	ds_read_b128 v[200:203], v199 offset:6144
	ds_read_b128 v[204:207], v199 offset:7168
	global_load_lds_dwordx4 v152, vcc
	s_add_i32 m0, s2, 0xe000
	s_nop 0
	global_load_lds_dwordx4 v154, vcc
	s_waitcnt vmcnt(8)
	s_waitcnt lgkmcnt(0)
	s_setprio 1
	s_barrier
; #define PG8_STAGE(bufoff, gbase, voff) do { _Pragma("unroll") for (int _i = 0; _i < 2; ++_i) \
;         __builtin_amdgcn_global_load_lds((const unsigned*)((const char*)(gbase) + (voff)[_i]), (PG8_LAS unsigned*)(lds + (bufoff) + ldsw + _i * 8192), 16, 0, 0); } while (0)
; #define PG8_LDA(dst, b, h) do { _Pragma("unroll") for (int m = 0; m < 4; ++m) _Pragma("unroll") for (int k = 0; k < 2; ++k) dst[m][k] = *(const PG8_LAS bf16x8*)(lds + PG8_SA(b, h) + aoff + m * 2048 + k * 1024); } while (0)
; #define PG8_MMA(ai, bj, At, Bt) do { __builtin_amdgcn_s_setprio(1); _Pragma("unroll") for (int m = 0; m < 4; ++m) _Pragma("unroll") for (int n = 0; n < 2; ++n) _Pragma("unroll") for (int k = 0; k < 2; ++k) \
;         acc[ai][bj][m][n] = __builtin_amdgcn_mfma_f32_16x16x32_bf16(Bt[n][k], At[m][k], acc[ai][bj][m][n], 0, 0, 0); __builtin_amdgcn_s_setprio(0); } while (0)
; #define PG8_WAIT_V(n) asm volatile("s_waitcnt vmcnt(" #n ")" ::: "memory")
; #define PG8_WAIT_L(n) asm volatile("s_waitcnt lgkmcnt(" #n ")" ::: "memory")
; #define PG8_BAR __builtin_amdgcn_s_barrier()
; #define PG8_SCHED __builtin_amdgcn_sched_barrier(0)
; template <class Epi, class Sched, bool ALIGN_EPI = false, bool SP2 = false>
; __device__ __forceinline__ void gemm_phase(PG8_LAS unsigned char* lds, const Gemm g, const Sched& S, const Epi& E) {
;     ...
;             PG8_WAIT_V(8); PG8_WAIT_L(0); PG8_BAR; PG8_MMA(0, 0, At, B0); PG8_MMA(0, 1, At, B1); PG8_BAR; PG8_SCHED;
;             PG8_LDA(At, 0, 1); PG8_STAGE(PG8_SB(0, 0), b2, voffB); PG8_STAGE(PG8_SB(0, 1), b2 + hstep, voffB); PG8_STAGE(PG8_SA(0, 0), a2, voffA);
;             PG8_WAIT_V(8); PG8_WAIT_L(0); PG8_BAR; PG8_MMA(1, 0, At, B0); PG8_MMA(1, 1, At, B1); PG8_BAR; PG8_SCHED;
	v_mfma_f32_16x16x32_bf16 v[142:145], v[114:117], v[168:171], v[142:145]
	v_mfma_f32_16x16x32_bf16 v[62:65], v[130:133], v[168:171], v[62:65]
	v_mfma_f32_16x16x32_bf16 v[122:125], v[114:117], v[176:179], v[122:125]
	v_mfma_f32_16x16x32_bf16 v[50:53], v[130:133], v[176:179], v[50:53]
	v_mfma_f32_16x16x32_bf16 v[106:109], v[114:117], v[184:187], v[106:109]
	v_mfma_f32_16x16x32_bf16 v[42:45], v[130:133], v[184:187], v[42:45]
	v_mfma_f32_16x16x32_bf16 v[98:101], v[114:117], v[200:203], v[98:101]
	v_mfma_f32_16x16x32_bf16 v[34:37], v[130:133], v[200:203], v[34:37]
	v_mfma_f32_16x16x32_bf16 v[142:145], v[118:121], v[172:175], v[142:145]
	v_mfma_f32_16x16x32_bf16 v[62:65], v[138:141], v[172:175], v[62:65]
	v_mfma_f32_16x16x32_bf16 v[122:125], v[118:121], v[180:183], v[122:125]
	v_mfma_f32_16x16x32_bf16 v[50:53], v[138:141], v[180:183], v[50:53]
	v_mfma_f32_16x16x32_bf16 v[106:109], v[118:121], v[188:191], v[106:109]
	v_mfma_f32_16x16x32_bf16 v[42:45], v[138:141], v[188:191], v[42:45]
	v_mfma_f32_16x16x32_bf16 v[98:101], v[118:121], v[204:207], v[98:101]
	v_mfma_f32_16x16x32_bf16 v[34:37], v[138:141], v[204:207], v[34:37]
	v_mfma_f32_16x16x32_bf16 v[134:137], v[146:149], v[168:171], v[134:137]
	v_mfma_f32_16x16x32_bf16 v[58:61], v[160:163], v[168:171], v[58:61]
	v_mfma_f32_16x16x32_bf16 v[126:129], v[146:149], v[176:179], v[126:129]
	v_mfma_f32_16x16x32_bf16 v[54:57], v[160:163], v[176:179], v[54:57]
	v_mfma_f32_16x16x32_bf16 v[110:113], v[146:149], v[184:187], v[110:113]
	v_mfma_f32_16x16x32_bf16 v[46:49], v[160:163], v[184:187], v[46:49]
	v_mfma_f32_16x16x32_bf16 v[102:105], v[146:149], v[200:203], v[102:105]
	v_mfma_f32_16x16x32_bf16 v[38:41], v[160:163], v[200:203], v[38:41]
	v_mfma_f32_16x16x32_bf16 v[134:137], v[156:159], v[172:175], v[134:137]
	v_mfma_f32_16x16x32_bf16 v[58:61], v[164:167], v[172:175], v[58:61]
	v_mfma_f32_16x16x32_bf16 v[126:129], v[156:159], v[180:183], v[126:129]
	v_mfma_f32_16x16x32_bf16 v[54:57], v[164:167], v[180:183], v[54:57]
	v_mfma_f32_16x16x32_bf16 v[110:113], v[156:159], v[188:191], v[110:113]
	v_mfma_f32_16x16x32_bf16 v[46:49], v[164:167], v[188:191], v[46:49]
	v_mfma_f32_16x16x32_bf16 v[102:105], v[156:159], v[204:207], v[102:105]
	v_mfma_f32_16x16x32_bf16 v[38:41], v[164:167], v[204:207], v[38:41]
	s_barrier
	s_setprio 0
	s_add_i32 s84, s84, s1
	s_add_u32 s100, s10, 0x80
	s_addc_u32 s101, s11, 0
	s_mov_b32 m0, s84
	ds_read_b128 v[168:171], v199 offset:16384
	ds_read_b128 v[172:175], v199 offset:17408
	ds_read_b128 v[176:179], v199 offset:18432
	ds_read_b128 v[180:183], v199 offset:19456
	ds_read_b128 v[184:187], v199 offset:20480
	ds_read_b128 v[188:191], v199 offset:21504
	ds_read_b128 v[200:203], v199 offset:22528
	ds_read_b128 v[204:207], v199 offset:23552
	global_load_lds_dwordx4 v0, s[10:11]
	s_add_i32 m0, s84, 0x2000
	s_add_u32 s84, s10, 0x80000
	s_addc_u32 s85, s11, 0
	s_add_i32 s93, s93, s1
	global_load_lds_dwordx4 v150, s[10:11]
	s_mov_b32 m0, s93
	s_add_u32 s98, s68, 0x80
	s_addc_u32 s99, s69, 0
	global_load_lds_dwordx4 v0, s[84:85]
	s_add_i32 m0, s93, 0x2000
	s_nop 0
	global_load_lds_dwordx4 v150, s[84:85]
	s_mov_b32 m0, s2
	s_nop 0
	global_load_lds_dwordx4 v0, s[68:69]
	s_mov_b32 m0, s4
	s_nop 0
	global_load_lds_dwordx4 v150, s[68:69]
	s_waitcnt vmcnt(8)
	s_waitcnt lgkmcnt(0)
	s_setprio 1
	s_barrier
	v_mfma_f32_16x16x32_bf16 v[94:97], v[114:117], v[168:171], v[94:97]
	v_mfma_f32_16x16x32_bf16 v[30:33], v[130:133], v[168:171], v[30:33]
	v_mfma_f32_16x16x32_bf16 v[82:85], v[114:117], v[176:179], v[82:85]
	v_mfma_f32_16x16x32_bf16 v[18:21], v[130:133], v[176:179], v[18:21]
	v_mfma_f32_16x16x32_bf16 v[74:77], v[114:117], v[184:187], v[74:77]
	v_mfma_f32_16x16x32_bf16 v[10:13], v[130:133], v[184:187], v[10:13]
	v_mfma_f32_16x16x32_bf16 v[66:69], v[114:117], v[200:203], v[66:69]
	v_mfma_f32_16x16x32_bf16 v[2:5], v[130:133], v[200:203], v[2:5]
	v_mfma_f32_16x16x32_bf16 v[94:97], v[118:121], v[172:175], v[94:97]
	v_mfma_f32_16x16x32_bf16 v[30:33], v[138:141], v[172:175], v[30:33]
	v_mfma_f32_16x16x32_bf16 v[82:85], v[118:121], v[180:183], v[82:85]
	v_mfma_f32_16x16x32_bf16 v[18:21], v[138:141], v[180:183], v[18:21]
	v_mfma_f32_16x16x32_bf16 v[74:77], v[118:121], v[188:191], v[74:77]
	v_mfma_f32_16x16x32_bf16 v[10:13], v[138:141], v[188:191], v[10:13]
	v_mfma_f32_16x16x32_bf16 v[66:69], v[118:121], v[204:207], v[66:69]
	v_mfma_f32_16x16x32_bf16 v[2:5], v[138:141], v[204:207], v[2:5]
	v_mfma_f32_16x16x32_bf16 v[90:93], v[146:149], v[168:171], v[90:93]
	v_mfma_f32_16x16x32_bf16 v[26:29], v[160:163], v[168:171], v[26:29]
	v_mfma_f32_16x16x32_bf16 v[86:89], v[146:149], v[176:179], v[86:89]
	v_mfma_f32_16x16x32_bf16 v[22:25], v[160:163], v[176:179], v[22:25]
	v_mfma_f32_16x16x32_bf16 v[78:81], v[146:149], v[184:187], v[78:81]
	v_mfma_f32_16x16x32_bf16 v[14:17], v[160:163], v[184:187], v[14:17]
	v_mfma_f32_16x16x32_bf16 v[70:73], v[146:149], v[200:203], v[70:73]
	v_mfma_f32_16x16x32_bf16 v[6:9], v[160:163], v[200:203], v[6:9]
	v_mfma_f32_16x16x32_bf16 v[90:93], v[156:159], v[172:175], v[90:93]
	v_mfma_f32_16x16x32_bf16 v[26:29], v[164:167], v[172:175], v[26:29]
	v_mfma_f32_16x16x32_bf16 v[86:89], v[156:159], v[180:183], v[86:89]
	v_mfma_f32_16x16x32_bf16 v[22:25], v[164:167], v[180:183], v[22:25]
	v_mfma_f32_16x16x32_bf16 v[78:81], v[156:159], v[188:191], v[78:81]
	v_mfma_f32_16x16x32_bf16 v[14:17], v[164:167], v[188:191], v[14:17]
	v_mfma_f32_16x16x32_bf16 v[70:73], v[156:159], v[204:207], v[70:73]
	v_mfma_f32_16x16x32_bf16 v[6:9], v[164:167], v[204:207], v[6:9]
	s_barrier
; #define PG8_STAGE(bufoff, gbase, voff) do { _Pragma("unroll") for (int _i = 0; _i < 2; ++_i) \
;         __builtin_amdgcn_global_load_lds((const unsigned*)((const char*)(gbase) + (voff)[_i]), (PG8_LAS unsigned*)(lds + (bufoff) + ldsw + _i * 8192), 16, 0, 0); } while (0)
; #define PG8_LDA(dst, b, h) do { _Pragma("unroll") for (int m = 0; m < 4; ++m) _Pragma("unroll") for (int k = 0; k < 2; ++k) dst[m][k] = *(const PG8_LAS bf16x8*)(lds + PG8_SA(b, h) + aoff + m * 2048 + k * 1024); } while (0)
; #define PG8_LDB(dst, b, h) do { _Pragma("unroll") for (int n = 0; n < 2; ++n) _Pragma("unroll") for (int k = 0; k < 2; ++k) dst[n][k] = *(const PG8_LAS bf16x8*)(lds + PG8_SB(b, h) + boff + n * 2048 + k * 1024); } while (0)
; #define PG8_MMA(ai, bj, At, Bt) do { __builtin_amdgcn_s_setprio(1); _Pragma("unroll") for (int m = 0; m < 4; ++m) _Pragma("unroll") for (int n = 0; n < 2; ++n) _Pragma("unroll") for (int k = 0; k < 2; ++k) \
;         acc[ai][bj][m][n] = __builtin_amdgcn_mfma_f32_16x16x32_bf16(Bt[n][k], At[m][k], acc[ai][bj][m][n], 0, 0, 0); __builtin_amdgcn_s_setprio(0); } while (0)
; #define PG8_WAIT_V(n) asm volatile("s_waitcnt vmcnt(" #n ")" ::: "memory")
; #define PG8_WAIT_L(n) asm volatile("s_waitcnt lgkmcnt(" #n ")" ::: "memory")
; #define PG8_BAR __builtin_amdgcn_s_barrier()
; #define PG8_SCHED __builtin_amdgcn_sched_barrier(0)
; template <class Epi, class Sched, bool ALIGN_EPI = false, bool SP2 = false>
; __device__ __forceinline__ void gemm_phase(PG8_LAS unsigned char* lds, const Gemm g, const Sched& S, const Epi& E) {
;     ...
;         for (int t = 0; t < nt; t += 2) {
;     ...
;             PG8_LDB(B0, 1, 0); PG8_LDB(B1, 1, 1); PG8_SCHED; PG8_LDA(At, 1, 0); PG8_STAGE(PG8_SA(0, 1), a2 + hstep, voffA);
;             PG8_WAIT_V(8); PG8_WAIT_L(0); PG8_BAR; PG8_MMA(0, 0, At, B0); PG8_MMA(0, 1, At, B1); PG8_BAR; PG8_SCHED;
;             PG8_LDA(At, 1, 1); PG8_STAGE(PG8_SB(1, 0), b3, voffB); PG8_STAGE(PG8_SB(1, 1), b3 + hstep, voffB); PG8_STAGE(PG8_SA(1, 0), a3, voffA);
;             PG8_WAIT_V(8); PG8_WAIT_L(0); PG8_BAR; PG8_MMA(1, 0, At, B0); PG8_MMA(1, 1, At, B1); PG8_BAR; PG8_SCHED;
	s_setprio 0
	s_add_i32 s84, 0, 0x18000
	s_add_i32 s85, 0, 0x1c000
	ds_read_b128 v[114:117], v218 offset:32768
	ds_read_b128 v[118:121], v218 offset:33792
	ds_read_b128 v[130:133], v218 offset:34816
	ds_read_b128 v[138:141], v218 offset:35840
	ds_read_b128 v[146:149], v218 offset:49152
	ds_read_b128 v[156:159], v218 offset:50176
	ds_read_b128 v[160:163], v218 offset:51200
	ds_read_b128 v[164:167], v218 offset:52224
	s_add_u32 s68, s68, 0x80000
	s_addc_u32 s69, s69, 0
	s_mov_b32 m0, s5
	ds_read_b128 v[168:171], v199 offset:32768
	ds_read_b128 v[172:175], v199 offset:33792
	ds_read_b128 v[176:179], v199 offset:34816
	ds_read_b128 v[180:183], v199 offset:35840
	ds_read_b128 v[184:187], v199 offset:36864
	ds_read_b128 v[188:191], v199 offset:37888
	ds_read_b128 v[200:203], v199 offset:38912
	ds_read_b128 v[204:207], v199 offset:39936
	global_load_lds_dwordx4 v0, s[68:69]
	s_mov_b32 m0, s6
	s_nop 0
	global_load_lds_dwordx4 v150, s[68:69]
	s_waitcnt vmcnt(8)
	s_waitcnt lgkmcnt(0)
	s_setprio 1
	s_barrier
	v_mfma_f32_16x16x32_bf16 v[142:145], v[114:117], v[168:171], v[142:145]
	v_mfma_f32_16x16x32_bf16 v[62:65], v[130:133], v[168:171], v[62:65]
	v_mfma_f32_16x16x32_bf16 v[122:125], v[114:117], v[176:179], v[122:125]
	v_mfma_f32_16x16x32_bf16 v[50:53], v[130:133], v[176:179], v[50:53]
	v_mfma_f32_16x16x32_bf16 v[106:109], v[114:117], v[184:187], v[106:109]
	v_mfma_f32_16x16x32_bf16 v[42:45], v[130:133], v[184:187], v[42:45]
	v_mfma_f32_16x16x32_bf16 v[98:101], v[114:117], v[200:203], v[98:101]
	v_mfma_f32_16x16x32_bf16 v[34:37], v[130:133], v[200:203], v[34:37]
	v_mfma_f32_16x16x32_bf16 v[142:145], v[118:121], v[172:175], v[142:145]
	v_mfma_f32_16x16x32_bf16 v[62:65], v[138:141], v[172:175], v[62:65]
	v_mfma_f32_16x16x32_bf16 v[122:125], v[118:121], v[180:183], v[122:125]
	v_mfma_f32_16x16x32_bf16 v[50:53], v[138:141], v[180:183], v[50:53]
	v_mfma_f32_16x16x32_bf16 v[106:109], v[118:121], v[188:191], v[106:109]
	v_mfma_f32_16x16x32_bf16 v[42:45], v[138:141], v[188:191], v[42:45]
	v_mfma_f32_16x16x32_bf16 v[98:101], v[118:121], v[204:207], v[98:101]
	v_mfma_f32_16x16x32_bf16 v[34:37], v[138:141], v[204:207], v[34:37]
	v_mfma_f32_16x16x32_bf16 v[134:137], v[146:149], v[168:171], v[134:137]
	v_mfma_f32_16x16x32_bf16 v[58:61], v[160:163], v[168:171], v[58:61]
	v_mfma_f32_16x16x32_bf16 v[126:129], v[146:149], v[176:179], v[126:129]
	v_mfma_f32_16x16x32_bf16 v[54:57], v[160:163], v[176:179], v[54:57]
	v_mfma_f32_16x16x32_bf16 v[110:113], v[146:149], v[184:187], v[110:113]
	v_mfma_f32_16x16x32_bf16 v[46:49], v[160:163], v[184:187], v[46:49]
	v_mfma_f32_16x16x32_bf16 v[102:105], v[146:149], v[200:203], v[102:105]
	v_mfma_f32_16x16x32_bf16 v[38:41], v[160:163], v[200:203], v[38:41]
	v_mfma_f32_16x16x32_bf16 v[134:137], v[156:159], v[172:175], v[134:137]
	v_mfma_f32_16x16x32_bf16 v[58:61], v[164:167], v[172:175], v[58:61]
	v_mfma_f32_16x16x32_bf16 v[126:129], v[156:159], v[180:183], v[126:129]
	v_mfma_f32_16x16x32_bf16 v[54:57], v[164:167], v[180:183], v[54:57]
	v_mfma_f32_16x16x32_bf16 v[110:113], v[156:159], v[188:191], v[110:113]
	v_mfma_f32_16x16x32_bf16 v[46:49], v[164:167], v[188:191], v[46:49]
	v_mfma_f32_16x16x32_bf16 v[102:105], v[156:159], v[204:207], v[102:105]
	v_mfma_f32_16x16x32_bf16 v[38:41], v[164:167], v[204:207], v[38:41]
	s_barrier
	s_setprio 0
	s_add_i32 s68, s84, s1
	s_mov_b32 m0, s68
	ds_read_b128 v[168:171], v199 offset:49152
	ds_read_b128 v[172:175], v199 offset:50176
	ds_read_b128 v[176:179], v199 offset:51200
	ds_read_b128 v[180:183], v199 offset:52224
	ds_read_b128 v[184:187], v199 offset:53248
	ds_read_b128 v[188:191], v199 offset:54272
	ds_read_b128 v[200:203], v199 offset:55296
	ds_read_b128 v[204:207], v199 offset:56320
	global_load_lds_dwordx4 v0, s[100:101]
	s_add_i32 m0, s68, 0x2000
	s_add_i32 s68, s85, s1
	global_load_lds_dwordx4 v150, s[100:101]
	s_add_u32 s10, s10, 0x80080
	s_addc_u32 s11, s11, 0
	s_mov_b32 m0, s68
	s_nop 0
	global_load_lds_dwordx4 v0, s[10:11]
	s_add_i32 m0, s68, 0x2000
	s_nop 0
	global_load_lds_dwordx4 v150, s[10:11]
	s_mov_b32 m0, s7
	s_nop 0
	global_load_lds_dwordx4 v0, s[98:99]
	s_mov_b32 m0, s30
	s_nop 0
	global_load_lds_dwordx4 v150, s[98:99]
	s_waitcnt vmcnt(8)
	s_waitcnt lgkmcnt(0)
	s_setprio 1
	s_barrier
	v_mfma_f32_16x16x32_bf16 v[94:97], v[114:117], v[168:171], v[94:97]
	v_mfma_f32_16x16x32_bf16 v[30:33], v[130:133], v[168:171], v[30:33]
	v_mfma_f32_16x16x32_bf16 v[82:85], v[114:117], v[176:179], v[82:85]
	v_mfma_f32_16x16x32_bf16 v[18:21], v[130:133], v[176:179], v[18:21]
	v_mfma_f32_16x16x32_bf16 v[74:77], v[114:117], v[184:187], v[74:77]
	v_mfma_f32_16x16x32_bf16 v[10:13], v[130:133], v[184:187], v[10:13]
	v_mfma_f32_16x16x32_bf16 v[66:69], v[114:117], v[200:203], v[66:69]
	v_mfma_f32_16x16x32_bf16 v[2:5], v[130:133], v[200:203], v[2:5]
	v_mfma_f32_16x16x32_bf16 v[94:97], v[118:121], v[172:175], v[94:97]
	v_mfma_f32_16x16x32_bf16 v[30:33], v[138:141], v[172:175], v[30:33]
	v_mfma_f32_16x16x32_bf16 v[82:85], v[118:121], v[180:183], v[82:85]
	v_mfma_f32_16x16x32_bf16 v[18:21], v[138:141], v[180:183], v[18:21]
	v_mfma_f32_16x16x32_bf16 v[74:77], v[118:121], v[188:191], v[74:77]
	v_mfma_f32_16x16x32_bf16 v[10:13], v[138:141], v[188:191], v[10:13]
	v_mfma_f32_16x16x32_bf16 v[66:69], v[118:121], v[204:207], v[66:69]
	v_mfma_f32_16x16x32_bf16 v[2:5], v[138:141], v[204:207], v[2:5]
	v_mfma_f32_16x16x32_bf16 v[90:93], v[146:149], v[168:171], v[90:93]
	v_mfma_f32_16x16x32_bf16 v[26:29], v[160:163], v[168:171], v[26:29]
	v_mfma_f32_16x16x32_bf16 v[86:89], v[146:149], v[176:179], v[86:89]
	v_mfma_f32_16x16x32_bf16 v[22:25], v[160:163], v[176:179], v[22:25]
	v_mfma_f32_16x16x32_bf16 v[78:81], v[146:149], v[184:187], v[78:81]
	v_mfma_f32_16x16x32_bf16 v[14:17], v[160:163], v[184:187], v[14:17]
	v_mfma_f32_16x16x32_bf16 v[70:73], v[146:149], v[200:203], v[70:73]
	v_mfma_f32_16x16x32_bf16 v[6:9], v[160:163], v[200:203], v[6:9]
	v_mfma_f32_16x16x32_bf16 v[90:93], v[156:159], v[172:175], v[90:93]
	v_mfma_f32_16x16x32_bf16 v[26:29], v[164:167], v[172:175], v[26:29]
	v_mfma_f32_16x16x32_bf16 v[86:89], v[156:159], v[180:183], v[86:89]
	v_mfma_f32_16x16x32_bf16 v[22:25], v[164:167], v[180:183], v[22:25]
	v_mfma_f32_16x16x32_bf16 v[78:81], v[156:159], v[188:191], v[78:81]
	v_mfma_f32_16x16x32_bf16 v[14:17], v[164:167], v[188:191], v[14:17]
	v_mfma_f32_16x16x32_bf16 v[70:73], v[156:159], v[204:207], v[70:73]
	v_mfma_f32_16x16x32_bf16 v[6:9], v[164:167], v[204:207], v[6:9]
	s_barrier
	s_setprio 0
	s_add_i32 s13, s13, 2
	s_add_u32 vcc_lo, vcc_lo, 0x100
	s_addc_u32 vcc_hi, vcc_hi, 0
	s_add_u32 s21, s21, 0x100
	s_addc_u32 s12, s12, 0
	s_cmp_gt_u32 s13, 29
	s_cbranch_scc0 .LBB0_38
	s_and_b64 vcc, exec, s[58:59]
	s_cbranch_vccz .LBB0_41
	s_barrier

; #define PG8_STAGE(bufoff, gbase, voff) do { _Pragma("unroll") for (int _i = 0; _i < 2; ++_i) \
;         __builtin_amdgcn_global_load_lds((const unsigned*)((const char*)(gbase) + (voff)[_i]), (PG8_LAS unsigned*)(lds + (bufoff) + ldsw + _i * 8192), 16, 0, 0); } while (0)
; #define PG8_LDA(dst, b, h) do { _Pragma("unroll") for (int m = 0; m < 4; ++m) _Pragma("unroll") for (int k = 0; k < 2; ++k) dst[m][k] = *(const PG8_LAS bf16x8*)(lds + PG8_SA(b, h) + aoff + m * 2048 + k * 1024); } while (0)
; #define PG8_LDB(dst, b, h) do { _Pragma("unroll") for (int n = 0; n < 2; ++n) _Pragma("unroll") for (int k = 0; k < 2; ++k) dst[n][k] = *(const PG8_LAS bf16x8*)(lds + PG8_SB(b, h) + boff + n * 2048 + k * 1024); } while (0)
; #define PG8_WAIT_V(n) asm volatile("s_waitcnt vmcnt(" #n ")" ::: "memory")
; #define PG8_WAIT_L(n) asm volatile("s_waitcnt lgkmcnt(" #n ")" ::: "memory")
; #define PG8_BAR __builtin_amdgcn_s_barrier()
; template <class Epi, class Sched, bool ALIGN_EPI = false, bool SP2 = false>
; __device__ __forceinline__ void gemm_phase(PG8_LAS unsigned char* lds, const Gemm g, const Sched& S, const Epi& E) {
;     ...
;         const bool has_next = S.next(ui + 1, nxt);
;         const char* nA = has_next ? (const char*)g.A + (size_t)nxt.pm * tstep : cA; const char* nB = has_next ? (const char*)g.Bt + (size_t)nxt.pn * tstep : cB;
;         for (int t = 0; t < nt; t += 2) {
;             const bool last = (t == nt - 2);
;             const char* a1 = cA + (size_t)(t + 1) * kstep;
;             const char* a2 = last ? nA : cA + (size_t)(t + 2) * kstep; const char* b2 = last ? nB : cB + (size_t)(t + 2) * kstep;
;             const char* a3 = a2 + kstep; const char* b3 = b2 + kstep;
;             if (last && has_next) S.a_ready(nxt);
;             if constexpr (SP2) {
;             PG8_LDB(B0, 0, 0); PG8_LDB(B1, 0, 1); PG8_SCHED; PG8_LDA(At, 0, 0); PG8_STAGE(PG8_SA(1, 1), a1 + hstep, voffA);
;             PG8_WAIT_V(8); PG8_WAIT_L(0); PG8_BAR; PG8_MMA(0, 0, At, B0); PG8_MMA(0, 1, At, B1); PG8_BAR; PG8_SCHED;
;     ...
; #pragma unroll
;         for (int a = 0; a < 2; ++a)
; #pragma unroll
;             for (int b = 0; b < 2; ++b)
; #pragma unroll
;                 for (int m = 0; m < 4; ++m)
; #pragma unroll
;                     for (int n = 0; n < 2; ++n) acc[a][b][m][n] = (f32x4){0.f, 0.f, 0.f, 0.f};
;         cur = nxt; cA = nA; cB = nB; ++ui;
.LBB0_222:
	s_add_u32 s8, s8, 0x80
	s_addc_u32 s9, s9, 0
	s_add_u32 s12, s10, 0x100
	v_mov_b32_e32 v2, 0
	s_addc_u32 s13, s11, 0
	s_mov_b32 s10, 0
	s_waitcnt lgkmcnt(0)
	v_mov_b32_e32 v3, v2
	v_mov_b32_e32 v4, v2
	v_mov_b32_e32 v5, v2
	v_mov_b32_e32 v6, v2
	v_mov_b32_e32 v7, v2
	v_mov_b32_e32 v8, v2
	v_mov_b32_e32 v9, v2
	v_mov_b32_e32 v18, v2
	v_mov_b32_e32 v19, v2
	v_mov_b32_e32 v20, v2
	v_mov_b32_e32 v21, v2
	v_mov_b32_e32 v22, v2
	v_mov_b32_e32 v23, v2
	v_mov_b32_e32 v24, v2
	v_mov_b32_e32 v25, v2
	v_mov_b32_e32 v34, v2
	v_mov_b32_e32 v35, v2
	v_mov_b32_e32 v36, v2
	v_mov_b32_e32 v37, v2
	v_mov_b32_e32 v38, v2
	v_mov_b32_e32 v39, v2
	v_mov_b32_e32 v40, v2
	v_mov_b32_e32 v41, v2
	v_mov_b32_e32 v50, v2
	v_mov_b32_e32 v51, v2
	v_mov_b32_e32 v52, v2
	v_mov_b32_e32 v53, v2
	v_mov_b32_e32 v54, v2
	v_mov_b32_e32 v55, v2
	v_mov_b32_e32 v56, v2
	v_mov_b32_e32 v57, v2
	v_mov_b32_e32 v10, v2
	v_mov_b32_e32 v11, v2
	v_mov_b32_e32 v12, v2
	v_mov_b32_e32 v13, v2
	v_mov_b32_e32 v14, v2
	v_mov_b32_e32 v15, v2
	v_mov_b32_e32 v16, v2
	v_mov_b32_e32 v17, v2
	v_mov_b32_e32 v26, v2
	v_mov_b32_e32 v27, v2
	v_mov_b32_e32 v28, v2
	v_mov_b32_e32 v29, v2
	v_mov_b32_e32 v30, v2
	v_mov_b32_e32 v31, v2
	v_mov_b32_e32 v32, v2
	v_mov_b32_e32 v33, v2
	v_mov_b32_e32 v42, v2
	v_mov_b32_e32 v43, v2
	v_mov_b32_e32 v44, v2
	v_mov_b32_e32 v45, v2
	v_mov_b32_e32 v46, v2
	v_mov_b32_e32 v47, v2
	v_mov_b32_e32 v48, v2
	v_mov_b32_e32 v49, v2
	v_mov_b32_e32 v58, v2
	v_mov_b32_e32 v59, v2
	v_mov_b32_e32 v60, v2
	v_mov_b32_e32 v61, v2
	v_mov_b32_e32 v62, v2
	v_mov_b32_e32 v63, v2
	v_mov_b32_e32 v64, v2
	v_mov_b32_e32 v65, v2
	v_mov_b32_e32 v66, v2
	v_mov_b32_e32 v67, v2
	v_mov_b32_e32 v68, v2
	v_mov_b32_e32 v69, v2
	v_mov_b32_e32 v70, v2
	v_mov_b32_e32 v71, v2
	v_mov_b32_e32 v72, v2
	v_mov_b32_e32 v73, v2
	v_mov_b32_e32 v82, v2
	v_mov_b32_e32 v83, v2
	v_mov_b32_e32 v84, v2
	v_mov_b32_e32 v85, v2
	v_mov_b32_e32 v86, v2
	v_mov_b32_e32 v87, v2
	v_mov_b32_e32 v88, v2
	v_mov_b32_e32 v89, v2
	v_mov_b32_e32 v98, v2
	v_mov_b32_e32 v99, v2
	v_mov_b32_e32 v100, v2
	v_mov_b32_e32 v101, v2
	v_mov_b32_e32 v102, v2
	v_mov_b32_e32 v103, v2
	v_mov_b32_e32 v104, v2
	v_mov_b32_e32 v105, v2
	v_mov_b32_e32 v114, v2
	v_mov_b32_e32 v115, v2
	v_mov_b32_e32 v116, v2
	v_mov_b32_e32 v117, v2
	v_mov_b32_e32 v118, v2
	v_mov_b32_e32 v119, v2
	v_mov_b32_e32 v120, v2
	v_mov_b32_e32 v121, v2
	v_mov_b32_e32 v74, v2
	v_mov_b32_e32 v75, v2
	v_mov_b32_e32 v76, v2
	v_mov_b32_e32 v77, v2
	v_mov_b32_e32 v78, v2
	v_mov_b32_e32 v79, v2
	v_mov_b32_e32 v80, v2
	v_mov_b32_e32 v81, v2
	v_mov_b32_e32 v90, v2
	v_mov_b32_e32 v91, v2
	v_mov_b32_e32 v92, v2
	v_mov_b32_e32 v93, v2
	v_mov_b32_e32 v94, v2
	v_mov_b32_e32 v95, v2
	v_mov_b32_e32 v96, v2
	v_mov_b32_e32 v97, v2
	v_mov_b32_e32 v106, v2
	v_mov_b32_e32 v107, v2
	v_mov_b32_e32 v108, v2
	v_mov_b32_e32 v109, v2
	v_mov_b32_e32 v110, v2
	v_mov_b32_e32 v111, v2
	v_mov_b32_e32 v112, v2
	v_mov_b32_e32 v113, v2
	v_mov_b32_e32 v122, v2
	v_mov_b32_e32 v123, v2
	v_mov_b32_e32 v124, v2
	v_mov_b32_e32 v125, v2
	v_mov_b32_e32 v126, v2
	v_mov_b32_e32 v127, v2
	v_mov_b32_e32 v128, v2
	v_mov_b32_e32 v129, v2
	v_add_u32_e32 v218, 0x10000, v145
.LBB0_223:
	s_add_i32 s14, s10, 2
	s_add_u32 s15, s8, 0x80
	s_addc_u32 s11, s9, 0
	s_add_i32 s64, 0, 0x10000
	s_cmp_eq_u32 s57, s10
	s_cselect_b32 s11, s51, s11
	s_cselect_b32 s10, s50, s15
	s_cselect_b32 s45, s53, s13
	s_cselect_b32 s44, s52, s12
	s_add_i32 s15, 0, 0x14000
	ds_read_b128 v[140:143], v218
	ds_read_b128 v[148:151], v218 offset:1024
	ds_read_b128 v[152:155], v218 offset:2048
	ds_read_b128 v[156:159], v218 offset:3072
	ds_read_b128 v[160:163], v218 offset:16384
	ds_read_b128 v[164:167], v218 offset:17408
	ds_read_b128 v[168:171], v218 offset:18432
	ds_read_b128 v[172:175], v218 offset:19456
	s_add_i32 m0, s21, 0xc000
	ds_read_b128 v[176:179], v147
	ds_read_b128 v[180:183], v147 offset:1024
	ds_read_b128 v[184:187], v147 offset:2048
	ds_read_b128 v[188:191], v147 offset:3072
	ds_read_b128 v[192:195], v147 offset:4096
	ds_read_b128 v[196:199], v147 offset:5120
	ds_read_b128 v[200:203], v147 offset:6144
	ds_read_b128 v[204:207], v147 offset:7168
	global_load_lds_dwordx4 v136, s[8:9]
	s_add_i32 m0, s21, 0xe000
	s_nop 0
	global_load_lds_dwordx4 v138, s[8:9]
	s_waitcnt vmcnt(8)
	s_waitcnt lgkmcnt(0)
	s_setprio 1
	s_barrier
	v_mfma_f32_16x16x32_bf16 v[126:129], v[140:143], v[176:179], v[126:129]
	v_mfma_f32_16x16x32_bf16 v[122:125], v[152:155], v[176:179], v[122:125]
	v_mfma_f32_16x16x32_bf16 v[110:113], v[140:143], v[184:187], v[110:113]
	v_mfma_f32_16x16x32_bf16 v[106:109], v[152:155], v[184:187], v[106:109]
	v_mfma_f32_16x16x32_bf16 v[94:97], v[140:143], v[192:195], v[94:97]
	v_mfma_f32_16x16x32_bf16 v[90:93], v[152:155], v[192:195], v[90:93]
	v_mfma_f32_16x16x32_bf16 v[78:81], v[140:143], v[200:203], v[78:81]
	v_mfma_f32_16x16x32_bf16 v[74:77], v[152:155], v[200:203], v[74:77]
	v_mfma_f32_16x16x32_bf16 v[126:129], v[148:151], v[180:183], v[126:129]
	v_mfma_f32_16x16x32_bf16 v[122:125], v[156:159], v[180:183], v[122:125]
	v_mfma_f32_16x16x32_bf16 v[110:113], v[148:151], v[188:191], v[110:113]
	v_mfma_f32_16x16x32_bf16 v[106:109], v[156:159], v[188:191], v[106:109]
	v_mfma_f32_16x16x32_bf16 v[94:97], v[148:151], v[196:199], v[94:97]
	v_mfma_f32_16x16x32_bf16 v[90:93], v[156:159], v[196:199], v[90:93]
	v_mfma_f32_16x16x32_bf16 v[78:81], v[148:151], v[204:207], v[78:81]
	v_mfma_f32_16x16x32_bf16 v[74:77], v[156:159], v[204:207], v[74:77]
	v_mfma_f32_16x16x32_bf16 v[118:121], v[160:163], v[176:179], v[118:121]
	v_mfma_f32_16x16x32_bf16 v[114:117], v[168:171], v[176:179], v[114:117]
	v_mfma_f32_16x16x32_bf16 v[102:105], v[160:163], v[184:187], v[102:105]
	v_mfma_f32_16x16x32_bf16 v[98:101], v[168:171], v[184:187], v[98:101]
	v_mfma_f32_16x16x32_bf16 v[86:89], v[160:163], v[192:195], v[86:89]
	v_mfma_f32_16x16x32_bf16 v[82:85], v[168:171], v[192:195], v[82:85]
	v_mfma_f32_16x16x32_bf16 v[70:73], v[160:163], v[200:203], v[70:73]
	v_mfma_f32_16x16x32_bf16 v[66:69], v[168:171], v[200:203], v[66:69]
	v_mfma_f32_16x16x32_bf16 v[118:121], v[164:167], v[180:183], v[118:121]
	v_mfma_f32_16x16x32_bf16 v[114:117], v[172:175], v[180:183], v[114:117]
	v_mfma_f32_16x16x32_bf16 v[102:105], v[164:167], v[188:191], v[102:105]
	v_mfma_f32_16x16x32_bf16 v[98:101], v[172:175], v[188:191], v[98:101]
	v_mfma_f32_16x16x32_bf16 v[86:89], v[164:167], v[196:199], v[86:89]
	v_mfma_f32_16x16x32_bf16 v[82:85], v[172:175], v[196:199], v[82:85]
	v_mfma_f32_16x16x32_bf16 v[70:73], v[164:167], v[204:207], v[70:73]
	v_mfma_f32_16x16x32_bf16 v[66:69], v[172:175], v[204:207], v[66:69]
	s_barrier
; #define PG8_STAGE(bufoff, gbase, voff) do { _Pragma("unroll") for (int _i = 0; _i < 2; ++_i) \
;         __builtin_amdgcn_global_load_lds((const unsigned*)((const char*)(gbase) + (voff)[_i]), (PG8_LAS unsigned*)(lds + (bufoff) + ldsw + _i * 8192), 16, 0, 0); } while (0)
; #define PG8_LDA(dst, b, h) do { _Pragma("unroll") for (int m = 0; m < 4; ++m) _Pragma("unroll") for (int k = 0; k < 2; ++k) dst[m][k] = *(const PG8_LAS bf16x8*)(lds + PG8_SA(b, h) + aoff + m * 2048 + k * 1024); } while (0)
; #define PG8_LDB(dst, b, h) do { _Pragma("unroll") for (int n = 0; n < 2; ++n) _Pragma("unroll") for (int k = 0; k < 2; ++k) dst[n][k] = *(const PG8_LAS bf16x8*)(lds + PG8_SB(b, h) + boff + n * 2048 + k * 1024); } while (0)
; #define PG8_MMA(ai, bj, At, Bt) do { __builtin_amdgcn_s_setprio(1); _Pragma("unroll") for (int m = 0; m < 4; ++m) _Pragma("unroll") for (int n = 0; n < 2; ++n) _Pragma("unroll") for (int k = 0; k < 2; ++k) \
;         acc[ai][bj][m][n] = __builtin_amdgcn_mfma_f32_16x16x32_bf16(Bt[n][k], At[m][k], acc[ai][bj][m][n], 0, 0, 0); __builtin_amdgcn_s_setprio(0); } while (0)
; #define PG8_WAIT_V(n) asm volatile("s_waitcnt vmcnt(" #n ")" ::: "memory")
; #define PG8_WAIT_L(n) asm volatile("s_waitcnt lgkmcnt(" #n ")" ::: "memory")
; #define PG8_BAR __builtin_amdgcn_s_barrier()
; #define PG8_SCHED __builtin_amdgcn_sched_barrier(0)
; template <class Epi, class Sched, bool ALIGN_EPI = false, bool SP2 = false>
; __device__ __forceinline__ void gemm_phase(PG8_LAS unsigned char* lds, const Gemm g, const Sched& S, const Epi& E) {
;     ...
;             PG8_LDA(At, 0, 1); PG8_STAGE(PG8_SB(0, 0), b2, voffB); PG8_STAGE(PG8_SB(0, 1), b2 + hstep, voffB); PG8_STAGE(PG8_SA(0, 0), a2, voffA);
;             PG8_WAIT_V(8); PG8_WAIT_L(0); PG8_BAR; PG8_MMA(1, 0, At, B0); PG8_MMA(1, 1, At, B1); PG8_BAR; PG8_SCHED;
;             PG8_LDB(B0, 1, 0); PG8_LDB(B1, 1, 1); PG8_SCHED; PG8_LDA(At, 1, 0); PG8_STAGE(PG8_SA(0, 1), a2 + hstep, voffA);
;             PG8_WAIT_V(8); PG8_WAIT_L(0); PG8_BAR; PG8_MMA(0, 0, At, B0); PG8_MMA(0, 1, At, B1); PG8_BAR; PG8_SCHED;
	s_setprio 0
	s_add_i32 s64, s64, s7
	s_add_u32 s98, s44, 0x80
	s_addc_u32 s99, s45, 0
	s_mov_b32 m0, s64
	ds_read_b128 v[176:179], v147 offset:16384
	ds_read_b128 v[180:183], v147 offset:17408
	ds_read_b128 v[184:187], v147 offset:18432
	ds_read_b128 v[188:191], v147 offset:19456
	ds_read_b128 v[192:195], v147 offset:20480
	ds_read_b128 v[196:199], v147 offset:21504
	ds_read_b128 v[200:203], v147 offset:22528
	ds_read_b128 v[204:207], v147 offset:23552
	global_load_lds_dwordx4 v0, s[44:45]
	s_add_i32 m0, s64, 0x2000
	s_add_i32 s15, s15, s7
	global_load_lds_dwordx4 v134, s[44:45]
	s_add_u32 s44, s44, s30
	s_addc_u32 s45, s45, 0
	s_add_u32 s100, s44, 0x80
	s_addc_u32 s101, s45, 0
	s_mov_b32 m0, s15
	s_add_u32 vcc_lo, s10, 0x80
	s_addc_u32 vcc_hi, s11, 0
	global_load_lds_dwordx4 v0, s[44:45]
	s_add_i32 m0, s15, 0x2000
	s_nop 0
	global_load_lds_dwordx4 v134, s[44:45]
	s_mov_b32 m0, s21
	s_nop 0
	global_load_lds_dwordx4 v130, s[10:11]
	s_mov_b32 m0, s26
	s_nop 0
	global_load_lds_dwordx4 v132, s[10:11]
	s_waitcnt vmcnt(8)
	s_waitcnt lgkmcnt(0)
	s_setprio 1
	s_barrier
	v_mfma_f32_16x16x32_bf16 v[62:65], v[140:143], v[176:179], v[62:65]
	v_mfma_f32_16x16x32_bf16 v[58:61], v[152:155], v[176:179], v[58:61]
	v_mfma_f32_16x16x32_bf16 v[46:49], v[140:143], v[184:187], v[46:49]
	v_mfma_f32_16x16x32_bf16 v[42:45], v[152:155], v[184:187], v[42:45]
	v_mfma_f32_16x16x32_bf16 v[30:33], v[140:143], v[192:195], v[30:33]
	v_mfma_f32_16x16x32_bf16 v[26:29], v[152:155], v[192:195], v[26:29]
	v_mfma_f32_16x16x32_bf16 v[14:17], v[140:143], v[200:203], v[14:17]
	v_mfma_f32_16x16x32_bf16 v[10:13], v[152:155], v[200:203], v[10:13]
	v_mfma_f32_16x16x32_bf16 v[62:65], v[148:151], v[180:183], v[62:65]
	v_mfma_f32_16x16x32_bf16 v[58:61], v[156:159], v[180:183], v[58:61]
	v_mfma_f32_16x16x32_bf16 v[46:49], v[148:151], v[188:191], v[46:49]
	v_mfma_f32_16x16x32_bf16 v[42:45], v[156:159], v[188:191], v[42:45]
	v_mfma_f32_16x16x32_bf16 v[30:33], v[148:151], v[196:199], v[30:33]
	v_mfma_f32_16x16x32_bf16 v[26:29], v[156:159], v[196:199], v[26:29]
	v_mfma_f32_16x16x32_bf16 v[14:17], v[148:151], v[204:207], v[14:17]
	v_mfma_f32_16x16x32_bf16 v[10:13], v[156:159], v[204:207], v[10:13]
	v_mfma_f32_16x16x32_bf16 v[54:57], v[160:163], v[176:179], v[54:57]
	v_mfma_f32_16x16x32_bf16 v[50:53], v[168:171], v[176:179], v[50:53]
	v_mfma_f32_16x16x32_bf16 v[38:41], v[160:163], v[184:187], v[38:41]
	v_mfma_f32_16x16x32_bf16 v[34:37], v[168:171], v[184:187], v[34:37]
	v_mfma_f32_16x16x32_bf16 v[22:25], v[160:163], v[192:195], v[22:25]
	v_mfma_f32_16x16x32_bf16 v[18:21], v[168:171], v[192:195], v[18:21]
	v_mfma_f32_16x16x32_bf16 v[6:9], v[160:163], v[200:203], v[6:9]
	v_mfma_f32_16x16x32_bf16 v[2:5], v[168:171], v[200:203], v[2:5]
	v_mfma_f32_16x16x32_bf16 v[54:57], v[164:167], v[180:183], v[54:57]
	v_mfma_f32_16x16x32_bf16 v[50:53], v[172:175], v[180:183], v[50:53]
	v_mfma_f32_16x16x32_bf16 v[38:41], v[164:167], v[188:191], v[38:41]
	v_mfma_f32_16x16x32_bf16 v[34:37], v[172:175], v[188:191], v[34:37]
	v_mfma_f32_16x16x32_bf16 v[22:25], v[164:167], v[196:199], v[22:25]
	v_mfma_f32_16x16x32_bf16 v[18:21], v[172:175], v[196:199], v[18:21]
	v_mfma_f32_16x16x32_bf16 v[6:9], v[164:167], v[204:207], v[6:9]
	v_mfma_f32_16x16x32_bf16 v[2:5], v[172:175], v[204:207], v[2:5]
	s_barrier
	s_setprio 0
	s_add_i32 s15, 0, 0x18000
	s_add_i32 s44, 0, 0x1c000
	ds_read_b128 v[140:143], v218 offset:32768
	ds_read_b128 v[148:151], v218 offset:33792
	ds_read_b128 v[152:155], v218 offset:34816
	ds_read_b128 v[156:159], v218 offset:35840
	ds_read_b128 v[160:163], v218 offset:49152
	ds_read_b128 v[164:167], v218 offset:50176
	ds_read_b128 v[168:171], v218 offset:51200
	ds_read_b128 v[172:175], v218 offset:52224
	s_add_u32 s10, s10, s30
	s_addc_u32 s11, s11, 0
	s_mov_b32 m0, s27
	ds_read_b128 v[176:179], v147 offset:32768
	ds_read_b128 v[180:183], v147 offset:33792
	ds_read_b128 v[184:187], v147 offset:34816
	ds_read_b128 v[188:191], v147 offset:35840
	ds_read_b128 v[192:195], v147 offset:36864
	ds_read_b128 v[196:199], v147 offset:37888
	ds_read_b128 v[200:203], v147 offset:38912
	ds_read_b128 v[204:207], v147 offset:39936
	global_load_lds_dwordx4 v130, s[10:11]
	s_mov_b32 m0, s54
	s_nop 0
	global_load_lds_dwordx4 v132, s[10:11]
	s_waitcnt vmcnt(8)
	s_waitcnt lgkmcnt(0)
	s_setprio 1
	s_barrier
; #define PG8_STAGE(bufoff, gbase, voff) do { _Pragma("unroll") for (int _i = 0; _i < 2; ++_i) \
;         __builtin_amdgcn_global_load_lds((const unsigned*)((const char*)(gbase) + (voff)[_i]), (PG8_LAS unsigned*)(lds + (bufoff) + ldsw + _i * 8192), 16, 0, 0); } while (0)
; #define PG8_LDA(dst, b, h) do { _Pragma("unroll") for (int m = 0; m < 4; ++m) _Pragma("unroll") for (int k = 0; k < 2; ++k) dst[m][k] = *(const PG8_LAS bf16x8*)(lds + PG8_SA(b, h) + aoff + m * 2048 + k * 1024); } while (0)
; #define PG8_MMA(ai, bj, At, Bt) do { __builtin_amdgcn_s_setprio(1); _Pragma("unroll") for (int m = 0; m < 4; ++m) _Pragma("unroll") for (int n = 0; n < 2; ++n) _Pragma("unroll") for (int k = 0; k < 2; ++k) \
;         acc[ai][bj][m][n] = __builtin_amdgcn_mfma_f32_16x16x32_bf16(Bt[n][k], At[m][k], acc[ai][bj][m][n], 0, 0, 0); __builtin_amdgcn_s_setprio(0); } while (0)
; #define PG8_WAIT_V(n) asm volatile("s_waitcnt vmcnt(" #n ")" ::: "memory")
; #define PG8_WAIT_L(n) asm volatile("s_waitcnt lgkmcnt(" #n ")" ::: "memory")
; #define PG8_BAR __builtin_amdgcn_s_barrier()
; #define PG8_SCHED __builtin_amdgcn_sched_barrier(0)
; template <class Epi, class Sched, bool ALIGN_EPI = false, bool SP2 = false>
; __device__ __forceinline__ void gemm_phase(PG8_LAS unsigned char* lds, const Gemm g, const Sched& S, const Epi& E) {
;     ...
;         for (int t = 0; t < nt; t += 2) {
;     ...
;             PG8_WAIT_V(8); PG8_WAIT_L(0); PG8_BAR; PG8_MMA(0, 0, At, B0); PG8_MMA(0, 1, At, B1); PG8_BAR; PG8_SCHED;
;             PG8_LDA(At, 1, 1); PG8_STAGE(PG8_SB(1, 0), b3, voffB); PG8_STAGE(PG8_SB(1, 1), b3 + hstep, voffB); PG8_STAGE(PG8_SA(1, 0), a3, voffA);
;             PG8_WAIT_V(8); PG8_WAIT_L(0); PG8_BAR; PG8_MMA(1, 0, At, B0); PG8_MMA(1, 1, At, B1); PG8_BAR; PG8_SCHED;
	v_mfma_f32_16x16x32_bf16 v[126:129], v[140:143], v[176:179], v[126:129]
	v_mfma_f32_16x16x32_bf16 v[122:125], v[152:155], v[176:179], v[122:125]
	v_mfma_f32_16x16x32_bf16 v[110:113], v[140:143], v[184:187], v[110:113]
	v_mfma_f32_16x16x32_bf16 v[106:109], v[152:155], v[184:187], v[106:109]
	v_mfma_f32_16x16x32_bf16 v[94:97], v[140:143], v[192:195], v[94:97]
	v_mfma_f32_16x16x32_bf16 v[90:93], v[152:155], v[192:195], v[90:93]
	v_mfma_f32_16x16x32_bf16 v[78:81], v[140:143], v[200:203], v[78:81]
	v_mfma_f32_16x16x32_bf16 v[74:77], v[152:155], v[200:203], v[74:77]
	v_mfma_f32_16x16x32_bf16 v[126:129], v[148:151], v[180:183], v[126:129]
	v_mfma_f32_16x16x32_bf16 v[122:125], v[156:159], v[180:183], v[122:125]
	v_mfma_f32_16x16x32_bf16 v[110:113], v[148:151], v[188:191], v[110:113]
	v_mfma_f32_16x16x32_bf16 v[106:109], v[156:159], v[188:191], v[106:109]
	v_mfma_f32_16x16x32_bf16 v[94:97], v[148:151], v[196:199], v[94:97]
	v_mfma_f32_16x16x32_bf16 v[90:93], v[156:159], v[196:199], v[90:93]
	v_mfma_f32_16x16x32_bf16 v[78:81], v[148:151], v[204:207], v[78:81]
	v_mfma_f32_16x16x32_bf16 v[74:77], v[156:159], v[204:207], v[74:77]
	v_mfma_f32_16x16x32_bf16 v[118:121], v[160:163], v[176:179], v[118:121]
	v_mfma_f32_16x16x32_bf16 v[114:117], v[168:171], v[176:179], v[114:117]
	v_mfma_f32_16x16x32_bf16 v[102:105], v[160:163], v[184:187], v[102:105]
	v_mfma_f32_16x16x32_bf16 v[98:101], v[168:171], v[184:187], v[98:101]
	v_mfma_f32_16x16x32_bf16 v[86:89], v[160:163], v[192:195], v[86:89]
	v_mfma_f32_16x16x32_bf16 v[82:85], v[168:171], v[192:195], v[82:85]
	v_mfma_f32_16x16x32_bf16 v[70:73], v[160:163], v[200:203], v[70:73]
	v_mfma_f32_16x16x32_bf16 v[66:69], v[168:171], v[200:203], v[66:69]
	v_mfma_f32_16x16x32_bf16 v[118:121], v[164:167], v[180:183], v[118:121]
	v_mfma_f32_16x16x32_bf16 v[114:117], v[172:175], v[180:183], v[114:117]
	v_mfma_f32_16x16x32_bf16 v[102:105], v[164:167], v[188:191], v[102:105]
	v_mfma_f32_16x16x32_bf16 v[98:101], v[172:175], v[188:191], v[98:101]
	v_mfma_f32_16x16x32_bf16 v[86:89], v[164:167], v[196:199], v[86:89]
	v_mfma_f32_16x16x32_bf16 v[82:85], v[172:175], v[196:199], v[82:85]
	v_mfma_f32_16x16x32_bf16 v[70:73], v[164:167], v[204:207], v[70:73]
	v_mfma_f32_16x16x32_bf16 v[66:69], v[172:175], v[204:207], v[66:69]
	s_barrier
	s_setprio 0
	s_add_i32 s10, s15, s7
	s_mov_b32 m0, s10
	ds_read_b128 v[176:179], v147 offset:49152
	ds_read_b128 v[180:183], v147 offset:50176
	ds_read_b128 v[184:187], v147 offset:51200
	ds_read_b128 v[188:191], v147 offset:52224
	ds_read_b128 v[192:195], v147 offset:53248
	ds_read_b128 v[196:199], v147 offset:54272
	ds_read_b128 v[200:203], v147 offset:55296
	ds_read_b128 v[204:207], v147 offset:56320
	global_load_lds_dwordx4 v0, s[98:99]
	s_add_i32 m0, s10, 0x2000
	s_add_i32 s10, s44, s7
	global_load_lds_dwordx4 v134, s[98:99]
	s_mov_b32 m0, s10
	s_nop 0
	global_load_lds_dwordx4 v0, s[100:101]
	s_add_i32 m0, s10, 0x2000
	s_nop 0
	global_load_lds_dwordx4 v134, s[100:101]
	s_mov_b32 m0, s16
	s_nop 0
	global_load_lds_dwordx4 v130, vcc
	s_mov_b32 m0, s17
	s_nop 0
	global_load_lds_dwordx4 v132, vcc
	s_waitcnt vmcnt(8)
	s_waitcnt lgkmcnt(0)
	s_setprio 1
	s_barrier
	v_mfma_f32_16x16x32_bf16 v[62:65], v[140:143], v[176:179], v[62:65]
	v_mfma_f32_16x16x32_bf16 v[58:61], v[152:155], v[176:179], v[58:61]
	v_mfma_f32_16x16x32_bf16 v[46:49], v[140:143], v[184:187], v[46:49]
	v_mfma_f32_16x16x32_bf16 v[42:45], v[152:155], v[184:187], v[42:45]
	v_mfma_f32_16x16x32_bf16 v[30:33], v[140:143], v[192:195], v[30:33]
	v_mfma_f32_16x16x32_bf16 v[26:29], v[152:155], v[192:195], v[26:29]
	v_mfma_f32_16x16x32_bf16 v[14:17], v[140:143], v[200:203], v[14:17]
	v_mfma_f32_16x16x32_bf16 v[10:13], v[152:155], v[200:203], v[10:13]
	v_mfma_f32_16x16x32_bf16 v[62:65], v[148:151], v[180:183], v[62:65]
	v_mfma_f32_16x16x32_bf16 v[58:61], v[156:159], v[180:183], v[58:61]
	v_mfma_f32_16x16x32_bf16 v[46:49], v[148:151], v[188:191], v[46:49]
	v_mfma_f32_16x16x32_bf16 v[42:45], v[156:159], v[188:191], v[42:45]
	v_mfma_f32_16x16x32_bf16 v[30:33], v[148:151], v[196:199], v[30:33]
	v_mfma_f32_16x16x32_bf16 v[26:29], v[156:159], v[196:199], v[26:29]
	v_mfma_f32_16x16x32_bf16 v[14:17], v[148:151], v[204:207], v[14:17]
	v_mfma_f32_16x16x32_bf16 v[10:13], v[156:159], v[204:207], v[10:13]
	v_mfma_f32_16x16x32_bf16 v[54:57], v[160:163], v[176:179], v[54:57]
	v_mfma_f32_16x16x32_bf16 v[50:53], v[168:171], v[176:179], v[50:53]
	v_mfma_f32_16x16x32_bf16 v[38:41], v[160:163], v[184:187], v[38:41]
	v_mfma_f32_16x16x32_bf16 v[34:37], v[168:171], v[184:187], v[34:37]
	v_mfma_f32_16x16x32_bf16 v[22:25], v[160:163], v[192:195], v[22:25]
	v_mfma_f32_16x16x32_bf16 v[18:21], v[168:171], v[192:195], v[18:21]
	v_mfma_f32_16x16x32_bf16 v[6:9], v[160:163], v[200:203], v[6:9]
	v_mfma_f32_16x16x32_bf16 v[2:5], v[168:171], v[200:203], v[2:5]
	v_mfma_f32_16x16x32_bf16 v[54:57], v[164:167], v[180:183], v[54:57]
	v_mfma_f32_16x16x32_bf16 v[50:53], v[172:175], v[180:183], v[50:53]
	v_mfma_f32_16x16x32_bf16 v[38:41], v[164:167], v[188:191], v[38:41]
	v_mfma_f32_16x16x32_bf16 v[34:37], v[172:175], v[188:191], v[34:37]
	v_mfma_f32_16x16x32_bf16 v[22:25], v[164:167], v[196:199], v[22:25]
	v_mfma_f32_16x16x32_bf16 v[18:21], v[172:175], v[196:199], v[18:21]
	v_mfma_f32_16x16x32_bf16 v[6:9], v[164:167], v[204:207], v[6:9]
	v_mfma_f32_16x16x32_bf16 v[2:5], v[172:175], v[204:207], v[2:5]
	s_barrier
	s_setprio 0
	s_add_u32 s8, s8, 0x100
	s_addc_u32 s9, s9, 0
	s_add_u32 s12, s12, 0x100
	s_addc_u32 s13, s13, 0
	s_cmp_ge_u32 s14, s56
	s_mov_b32 s10, s14
	s_cbranch_scc0 .LBB0_223
	s_and_b64 vcc, exec, s[46:47]
	s_cbranch_vccz .LBB0_226
	s_barrier

; #define PG8_STAGE(bufoff, gbase, voff) do { _Pragma("unroll") for (int _i = 0; _i < 2; ++_i) \
;         __builtin_amdgcn_global_load_lds((const unsigned*)((const char*)(gbase) + (voff)[_i]), (PG8_LAS unsigned*)(lds + (bufoff) + ldsw + _i * 8192), 16, 0, 0); } while (0)
; #define PG8_LDA(dst, b, h) do { _Pragma("unroll") for (int m = 0; m < 4; ++m) _Pragma("unroll") for (int k = 0; k < 2; ++k) dst[m][k] = *(const PG8_LAS bf16x8*)(lds + PG8_SA(b, h) + aoff + m * 2048 + k * 1024); } while (0)
; #define PG8_LDB(dst, b, h) do { _Pragma("unroll") for (int n = 0; n < 2; ++n) _Pragma("unroll") for (int k = 0; k < 2; ++k) dst[n][k] = *(const PG8_LAS bf16x8*)(lds + PG8_SB(b, h) + boff + n * 2048 + k * 1024); } while (0)
; #define PG8_WAIT_V(n) asm volatile("s_waitcnt vmcnt(" #n ")" ::: "memory")
; #define PG8_WAIT_L(n) asm volatile("s_waitcnt lgkmcnt(" #n ")" ::: "memory")
; #define PG8_BAR __builtin_amdgcn_s_barrier()
; #define PG8_SCHED __builtin_amdgcn_sched_barrier(0)
; template <class Epi, class Sched, bool ALIGN_EPI = false, bool SP2 = false>
; __device__ __forceinline__ void gemm_phase(PG8_LAS unsigned char* lds, const Gemm g, const Sched& S, const Epi& E) {
;     ...
;     f32x4 acc[2][2][4][2];
; #pragma unroll
;     for (int a = 0; a < 2; ++a)
; #pragma unroll
;         for (int b = 0; b < 2; ++b)
; #pragma unroll
;             for (int m = 0; m < 4; ++m)
; #pragma unroll
;                 for (int n = 0; n < 2; ++n) acc[a][b][m][n] = (f32x4){0.f, 0.f, 0.f, 0.f};
;     ...
;         const bool has_next = S.next(ui + 1, nxt);
;         const char* nA = has_next ? (const char*)g.A + (size_t)nxt.pm * tstep : cA; const char* nB = has_next ? (const char*)g.Bt + (size_t)nxt.pn * tstep : cB;
;         for (int t = 0; t < nt; t += 2) {
;             const bool last = (t == nt - 2);
;             const char* a1 = cA + (size_t)(t + 1) * kstep;
;             const char* a2 = last ? nA : cA + (size_t)(t + 2) * kstep; const char* b2 = last ? nB : cB + (size_t)(t + 2) * kstep;
;             const char* a3 = a2 + kstep; const char* b3 = b2 + kstep;
;             if (last && has_next) S.a_ready(nxt);
;             if constexpr (SP2) {
;             PG8_LDB(B0, 0, 0); PG8_LDB(B1, 0, 1); PG8_SCHED; PG8_LDA(At, 0, 0); PG8_STAGE(PG8_SA(1, 1), a1 + hstep, voffA);
;             PG8_WAIT_V(8); PG8_WAIT_L(0); PG8_BAR; PG8_MMA(0, 0, At, B0); PG8_MMA(0, 1, At, B1); PG8_BAR; PG8_SCHED;
.Lstg4_done:
	s_ashr_i32 s37, s36, 31
	s_lshl_b64 s[26:27], s[36:37], 20
	s_add_u32 s26, s18, s26
	s_addc_u32 s27, s19, s27
	s_and_b64 s[44:45], s[40:41], exec
	s_cselect_b32 s37, s27, s51
	s_cselect_b32 s43, s26, s50
	s_ashr_i32 s23, s22, 31
	s_lshl_b64 s[44:45], s[22:23], 20
	s_add_u32 s44, s96, s44
	s_addc_u32 s45, s97, s45
	s_and_b64 s[52:53], s[40:41], exec
	s_cselect_b32 s23, s45, s11
	s_cselect_b32 s56, s44, s10
	s_add_u32 s50, s50, 0x80080
	s_addc_u32 s51, s51, 0
	s_add_u32 s57, s10, 0x100
	v_mov_b32_e32 v2, 0
	s_addc_u32 s58, s11, 0
	s_mov_b32 s59, -2
	v_mov_b32_e32 v3, v2
	v_mov_b32_e32 v4, v2
	v_mov_b32_e32 v5, v2
	v_mov_b32_e32 v6, v2
	v_mov_b32_e32 v7, v2
	v_mov_b32_e32 v8, v2
	v_mov_b32_e32 v9, v2
	v_mov_b32_e32 v18, v2
	v_mov_b32_e32 v19, v2
	v_mov_b32_e32 v20, v2
	v_mov_b32_e32 v21, v2
	v_mov_b32_e32 v22, v2
	v_mov_b32_e32 v23, v2
	v_mov_b32_e32 v24, v2
	v_mov_b32_e32 v25, v2
	v_mov_b32_e32 v34, v2
	v_mov_b32_e32 v35, v2
	v_mov_b32_e32 v36, v2
	v_mov_b32_e32 v37, v2
	v_mov_b32_e32 v38, v2
	v_mov_b32_e32 v39, v2
	v_mov_b32_e32 v40, v2
	v_mov_b32_e32 v41, v2
	v_mov_b32_e32 v50, v2
	v_mov_b32_e32 v51, v2
	v_mov_b32_e32 v52, v2
	v_mov_b32_e32 v53, v2
	v_mov_b32_e32 v54, v2
	v_mov_b32_e32 v55, v2
	v_mov_b32_e32 v56, v2
	v_mov_b32_e32 v57, v2
	v_mov_b32_e32 v10, v2
	v_mov_b32_e32 v11, v2
	v_mov_b32_e32 v12, v2
	v_mov_b32_e32 v13, v2
	v_mov_b32_e32 v14, v2
	v_mov_b32_e32 v15, v2
	v_mov_b32_e32 v16, v2
	v_mov_b32_e32 v17, v2
	v_mov_b32_e32 v26, v2
	v_mov_b32_e32 v27, v2
	v_mov_b32_e32 v28, v2
	v_mov_b32_e32 v29, v2
	v_mov_b32_e32 v30, v2
	v_mov_b32_e32 v31, v2
	v_mov_b32_e32 v32, v2
	v_mov_b32_e32 v33, v2
	v_mov_b32_e32 v42, v2
	v_mov_b32_e32 v43, v2
	v_mov_b32_e32 v44, v2
	v_mov_b32_e32 v45, v2
	v_mov_b32_e32 v46, v2
	v_mov_b32_e32 v47, v2
	v_mov_b32_e32 v48, v2
	v_mov_b32_e32 v49, v2
	v_mov_b32_e32 v58, v2
	v_mov_b32_e32 v59, v2
	v_mov_b32_e32 v60, v2
	v_mov_b32_e32 v61, v2
	v_mov_b32_e32 v62, v2
	v_mov_b32_e32 v63, v2
	v_mov_b32_e32 v64, v2
	v_mov_b32_e32 v65, v2
	v_mov_b32_e32 v66, v2
	v_mov_b32_e32 v67, v2
	v_mov_b32_e32 v68, v2
	v_mov_b32_e32 v69, v2
	v_mov_b32_e32 v70, v2
	v_mov_b32_e32 v71, v2
	v_mov_b32_e32 v72, v2
	v_mov_b32_e32 v73, v2
	v_mov_b32_e32 v82, v2
	v_mov_b32_e32 v83, v2
	v_mov_b32_e32 v84, v2
	v_mov_b32_e32 v85, v2
	v_mov_b32_e32 v86, v2
	v_mov_b32_e32 v87, v2
	v_mov_b32_e32 v88, v2
	v_mov_b32_e32 v89, v2
	v_mov_b32_e32 v98, v2
	v_mov_b32_e32 v99, v2
	v_mov_b32_e32 v100, v2
	v_mov_b32_e32 v101, v2
	v_mov_b32_e32 v102, v2
	v_mov_b32_e32 v103, v2
	v_mov_b32_e32 v104, v2
	v_mov_b32_e32 v105, v2
	v_mov_b32_e32 v114, v2
	v_mov_b32_e32 v115, v2
	v_mov_b32_e32 v116, v2
	v_mov_b32_e32 v117, v2
	v_mov_b32_e32 v118, v2
	v_mov_b32_e32 v119, v2
	v_mov_b32_e32 v120, v2
	v_mov_b32_e32 v121, v2
	v_mov_b32_e32 v74, v2
	v_mov_b32_e32 v75, v2
	v_mov_b32_e32 v76, v2
	v_mov_b32_e32 v77, v2
	v_mov_b32_e32 v78, v2
	v_mov_b32_e32 v79, v2
	v_mov_b32_e32 v80, v2
	v_mov_b32_e32 v81, v2
	v_mov_b32_e32 v90, v2
	v_mov_b32_e32 v91, v2
	v_mov_b32_e32 v92, v2
	v_mov_b32_e32 v93, v2
	v_mov_b32_e32 v94, v2
	v_mov_b32_e32 v95, v2
	v_mov_b32_e32 v96, v2
	v_mov_b32_e32 v97, v2
	v_mov_b32_e32 v106, v2
	v_mov_b32_e32 v107, v2
	v_mov_b32_e32 v108, v2
	v_mov_b32_e32 v109, v2
	v_mov_b32_e32 v110, v2
	v_mov_b32_e32 v111, v2
	v_mov_b32_e32 v112, v2
	v_mov_b32_e32 v113, v2
	v_mov_b32_e32 v122, v2
	v_mov_b32_e32 v123, v2
	v_mov_b32_e32 v124, v2
	v_mov_b32_e32 v125, v2
	v_mov_b32_e32 v126, v2
	v_mov_b32_e32 v127, v2
	v_mov_b32_e32 v128, v2
	v_mov_b32_e32 v129, v2
	v_add_u32_e32 v248, 0x10000, v149
.LBB0_559:
	s_add_u32 s10, s50, 0xfff80080
	s_addc_u32 s11, s51, -1
	s_add_i32 s60, 0, 0x10000
	s_cmp_eq_u32 s59, 28
	s_cselect_b32 s53, s37, s11
	s_cselect_b32 s52, s43, s10
	s_cselect_b32 s11, s23, s58
	s_cselect_b32 s10, s56, s57
	s_add_i32 s62, 0, 0x14000
	ds_read_b128 v[140:143], v248
	ds_read_b128 v[152:155], v248 offset:1024
	ds_read_b128 v[156:159], v248 offset:2048
	ds_read_b128 v[160:163], v248 offset:3072
	ds_read_b128 v[164:167], v248 offset:16384
	ds_read_b128 v[168:171], v248 offset:17408
	ds_read_b128 v[172:175], v248 offset:18432
	ds_read_b128 v[176:179], v248 offset:19456
	s_add_i32 m0, s5, 0xc000
	ds_read_b128 v[180:183], v151
	ds_read_b128 v[184:187], v151 offset:1024
	ds_read_b128 v[188:191], v151 offset:2048
	ds_read_b128 v[192:195], v151 offset:3072
	ds_read_b128 v[196:199], v151 offset:4096
	ds_read_b128 v[200:203], v151 offset:5120
	ds_read_b128 v[204:207], v151 offset:6144
	ds_read_b128 v[208:211], v151 offset:7168
	global_load_lds_dwordx4 v136, s[50:51]
	s_add_i32 m0, s5, 0xe000
	s_nop 0
	global_load_lds_dwordx4 v138, s[50:51]
	s_waitcnt vmcnt(8)
	s_waitcnt lgkmcnt(0)
	s_setprio 1
	s_barrier
; #define PG8_STAGE(bufoff, gbase, voff) do { _Pragma("unroll") for (int _i = 0; _i < 2; ++_i) \
;         __builtin_amdgcn_global_load_lds((const unsigned*)((const char*)(gbase) + (voff)[_i]), (PG8_LAS unsigned*)(lds + (bufoff) + ldsw + _i * 8192), 16, 0, 0); } while (0)
; #define PG8_LDA(dst, b, h) do { _Pragma("unroll") for (int m = 0; m < 4; ++m) _Pragma("unroll") for (int k = 0; k < 2; ++k) dst[m][k] = *(const PG8_LAS bf16x8*)(lds + PG8_SA(b, h) + aoff + m * 2048 + k * 1024); } while (0)
; #define PG8_MMA(ai, bj, At, Bt) do { __builtin_amdgcn_s_setprio(1); _Pragma("unroll") for (int m = 0; m < 4; ++m) _Pragma("unroll") for (int n = 0; n < 2; ++n) _Pragma("unroll") for (int k = 0; k < 2; ++k) \
;         acc[ai][bj][m][n] = __builtin_amdgcn_mfma_f32_16x16x32_bf16(Bt[n][k], At[m][k], acc[ai][bj][m][n], 0, 0, 0); __builtin_amdgcn_s_setprio(0); } while (0)
; #define PG8_WAIT_V(n) asm volatile("s_waitcnt vmcnt(" #n ")" ::: "memory")
; #define PG8_WAIT_L(n) asm volatile("s_waitcnt lgkmcnt(" #n ")" ::: "memory")
; #define PG8_BAR __builtin_amdgcn_s_barrier()
; #define PG8_SCHED __builtin_amdgcn_sched_barrier(0)
; template <class Epi, class Sched, bool ALIGN_EPI = false, bool SP2 = false>
; __device__ __forceinline__ void gemm_phase(PG8_LAS unsigned char* lds, const Gemm g, const Sched& S, const Epi& E) {
;     ...
;             PG8_WAIT_V(8); PG8_WAIT_L(0); PG8_BAR; PG8_MMA(0, 0, At, B0); PG8_MMA(0, 1, At, B1); PG8_BAR; PG8_SCHED;
;             PG8_LDA(At, 0, 1); PG8_STAGE(PG8_SB(0, 0), b2, voffB); PG8_STAGE(PG8_SB(0, 1), b2 + hstep, voffB); PG8_STAGE(PG8_SA(0, 0), a2, voffA);
;             PG8_WAIT_V(8); PG8_WAIT_L(0); PG8_BAR; PG8_MMA(1, 0, At, B0); PG8_MMA(1, 1, At, B1); PG8_BAR; PG8_SCHED;
	v_mfma_f32_16x16x32_bf16 v[126:129], v[140:143], v[180:183], v[126:129]
	v_mfma_f32_16x16x32_bf16 v[122:125], v[156:159], v[180:183], v[122:125]
	v_mfma_f32_16x16x32_bf16 v[110:113], v[140:143], v[188:191], v[110:113]
	v_mfma_f32_16x16x32_bf16 v[106:109], v[156:159], v[188:191], v[106:109]
	v_mfma_f32_16x16x32_bf16 v[94:97], v[140:143], v[196:199], v[94:97]
	v_mfma_f32_16x16x32_bf16 v[90:93], v[156:159], v[196:199], v[90:93]
	v_mfma_f32_16x16x32_bf16 v[78:81], v[140:143], v[204:207], v[78:81]
	v_mfma_f32_16x16x32_bf16 v[74:77], v[156:159], v[204:207], v[74:77]
	v_mfma_f32_16x16x32_bf16 v[126:129], v[152:155], v[184:187], v[126:129]
	v_mfma_f32_16x16x32_bf16 v[122:125], v[160:163], v[184:187], v[122:125]
	v_mfma_f32_16x16x32_bf16 v[110:113], v[152:155], v[192:195], v[110:113]
	v_mfma_f32_16x16x32_bf16 v[106:109], v[160:163], v[192:195], v[106:109]
	v_mfma_f32_16x16x32_bf16 v[94:97], v[152:155], v[200:203], v[94:97]
	v_mfma_f32_16x16x32_bf16 v[90:93], v[160:163], v[200:203], v[90:93]
	v_mfma_f32_16x16x32_bf16 v[78:81], v[152:155], v[208:211], v[78:81]
	v_mfma_f32_16x16x32_bf16 v[74:77], v[160:163], v[208:211], v[74:77]
	v_mfma_f32_16x16x32_bf16 v[118:121], v[164:167], v[180:183], v[118:121]
	v_mfma_f32_16x16x32_bf16 v[114:117], v[172:175], v[180:183], v[114:117]
	v_mfma_f32_16x16x32_bf16 v[102:105], v[164:167], v[188:191], v[102:105]
	v_mfma_f32_16x16x32_bf16 v[98:101], v[172:175], v[188:191], v[98:101]
	v_mfma_f32_16x16x32_bf16 v[86:89], v[164:167], v[196:199], v[86:89]
	v_mfma_f32_16x16x32_bf16 v[82:85], v[172:175], v[196:199], v[82:85]
	v_mfma_f32_16x16x32_bf16 v[70:73], v[164:167], v[204:207], v[70:73]
	v_mfma_f32_16x16x32_bf16 v[66:69], v[172:175], v[204:207], v[66:69]
	v_mfma_f32_16x16x32_bf16 v[118:121], v[168:171], v[184:187], v[118:121]
	v_mfma_f32_16x16x32_bf16 v[114:117], v[176:179], v[184:187], v[114:117]
	v_mfma_f32_16x16x32_bf16 v[102:105], v[168:171], v[192:195], v[102:105]
	v_mfma_f32_16x16x32_bf16 v[98:101], v[176:179], v[192:195], v[98:101]
	v_mfma_f32_16x16x32_bf16 v[86:89], v[168:171], v[200:203], v[86:89]
	v_mfma_f32_16x16x32_bf16 v[82:85], v[176:179], v[200:203], v[82:85]
	v_mfma_f32_16x16x32_bf16 v[70:73], v[168:171], v[208:211], v[70:73]
	v_mfma_f32_16x16x32_bf16 v[66:69], v[176:179], v[208:211], v[66:69]
	s_barrier
	s_setprio 0
	s_add_i32 s60, s60, s4
	s_add_u32 s100, s10, 0x80
	s_addc_u32 s101, s11, 0
	s_mov_b32 m0, s60
	ds_read_b128 v[180:183], v151 offset:16384
	ds_read_b128 v[184:187], v151 offset:17408
	ds_read_b128 v[188:191], v151 offset:18432
	ds_read_b128 v[192:195], v151 offset:19456
	ds_read_b128 v[196:199], v151 offset:20480
	ds_read_b128 v[200:203], v151 offset:21504
	ds_read_b128 v[204:207], v151 offset:22528
	ds_read_b128 v[208:211], v151 offset:23552
	global_load_lds_dwordx4 v0, s[10:11]
	s_add_i32 m0, s60, 0x2000
	s_add_u32 s60, s10, 0x80000
	s_addc_u32 s61, s11, 0
	s_add_i32 s62, s62, s4
	global_load_lds_dwordx4 v134, s[10:11]
	s_mov_b32 m0, s62
	s_add_u32 s98, s52, 0x80
	s_addc_u32 s99, s53, 0
	global_load_lds_dwordx4 v0, s[60:61]
	s_add_i32 m0, s62, 0x2000
	s_nop 0
	global_load_lds_dwordx4 v134, s[60:61]
	s_mov_b32 m0, s5
	s_nop 0
	global_load_lds_dwordx4 v130, s[52:53]
	s_mov_b32 m0, s6
	s_nop 0
	global_load_lds_dwordx4 v132, s[52:53]
	s_waitcnt vmcnt(8)
	s_waitcnt lgkmcnt(0)
	s_setprio 1
	s_barrier
	v_mfma_f32_16x16x32_bf16 v[62:65], v[140:143], v[180:183], v[62:65]
	v_mfma_f32_16x16x32_bf16 v[58:61], v[156:159], v[180:183], v[58:61]
	v_mfma_f32_16x16x32_bf16 v[46:49], v[140:143], v[188:191], v[46:49]
	v_mfma_f32_16x16x32_bf16 v[42:45], v[156:159], v[188:191], v[42:45]
	v_mfma_f32_16x16x32_bf16 v[30:33], v[140:143], v[196:199], v[30:33]
	v_mfma_f32_16x16x32_bf16 v[26:29], v[156:159], v[196:199], v[26:29]
	v_mfma_f32_16x16x32_bf16 v[14:17], v[140:143], v[204:207], v[14:17]
	v_mfma_f32_16x16x32_bf16 v[10:13], v[156:159], v[204:207], v[10:13]
	v_mfma_f32_16x16x32_bf16 v[62:65], v[152:155], v[184:187], v[62:65]
	v_mfma_f32_16x16x32_bf16 v[58:61], v[160:163], v[184:187], v[58:61]
	v_mfma_f32_16x16x32_bf16 v[46:49], v[152:155], v[192:195], v[46:49]
	v_mfma_f32_16x16x32_bf16 v[42:45], v[160:163], v[192:195], v[42:45]
	v_mfma_f32_16x16x32_bf16 v[30:33], v[152:155], v[200:203], v[30:33]
	v_mfma_f32_16x16x32_bf16 v[26:29], v[160:163], v[200:203], v[26:29]
	v_mfma_f32_16x16x32_bf16 v[14:17], v[152:155], v[208:211], v[14:17]
	v_mfma_f32_16x16x32_bf16 v[10:13], v[160:163], v[208:211], v[10:13]
	v_mfma_f32_16x16x32_bf16 v[54:57], v[164:167], v[180:183], v[54:57]
	v_mfma_f32_16x16x32_bf16 v[50:53], v[172:175], v[180:183], v[50:53]
	v_mfma_f32_16x16x32_bf16 v[38:41], v[164:167], v[188:191], v[38:41]
	v_mfma_f32_16x16x32_bf16 v[34:37], v[172:175], v[188:191], v[34:37]
	v_mfma_f32_16x16x32_bf16 v[22:25], v[164:167], v[196:199], v[22:25]
	v_mfma_f32_16x16x32_bf16 v[18:21], v[172:175], v[196:199], v[18:21]
	v_mfma_f32_16x16x32_bf16 v[6:9], v[164:167], v[204:207], v[6:9]
	v_mfma_f32_16x16x32_bf16 v[2:5], v[172:175], v[204:207], v[2:5]
	v_mfma_f32_16x16x32_bf16 v[54:57], v[168:171], v[184:187], v[54:57]
	v_mfma_f32_16x16x32_bf16 v[50:53], v[176:179], v[184:187], v[50:53]
	v_mfma_f32_16x16x32_bf16 v[38:41], v[168:171], v[192:195], v[38:41]
	v_mfma_f32_16x16x32_bf16 v[34:37], v[176:179], v[192:195], v[34:37]
	v_mfma_f32_16x16x32_bf16 v[22:25], v[168:171], v[200:203], v[22:25]
	v_mfma_f32_16x16x32_bf16 v[18:21], v[176:179], v[200:203], v[18:21]
	v_mfma_f32_16x16x32_bf16 v[6:9], v[168:171], v[208:211], v[6:9]
	v_mfma_f32_16x16x32_bf16 v[2:5], v[176:179], v[208:211], v[2:5]
	s_barrier
; #define PG8_STAGE(bufoff, gbase, voff) do { _Pragma("unroll") for (int _i = 0; _i < 2; ++_i) \
;         __builtin_amdgcn_global_load_lds((const unsigned*)((const char*)(gbase) + (voff)[_i]), (PG8_LAS unsigned*)(lds + (bufoff) + ldsw + _i * 8192), 16, 0, 0); } while (0)
; #define PG8_LDA(dst, b, h) do { _Pragma("unroll") for (int m = 0; m < 4; ++m) _Pragma("unroll") for (int k = 0; k < 2; ++k) dst[m][k] = *(const PG8_LAS bf16x8*)(lds + PG8_SA(b, h) + aoff + m * 2048 + k * 1024); } while (0)
; #define PG8_LDB(dst, b, h) do { _Pragma("unroll") for (int n = 0; n < 2; ++n) _Pragma("unroll") for (int k = 0; k < 2; ++k) dst[n][k] = *(const PG8_LAS bf16x8*)(lds + PG8_SB(b, h) + boff + n * 2048 + k * 1024); } while (0)
; #define PG8_MMA(ai, bj, At, Bt) do { __builtin_amdgcn_s_setprio(1); _Pragma("unroll") for (int m = 0; m < 4; ++m) _Pragma("unroll") for (int n = 0; n < 2; ++n) _Pragma("unroll") for (int k = 0; k < 2; ++k) \
;         acc[ai][bj][m][n] = __builtin_amdgcn_mfma_f32_16x16x32_bf16(Bt[n][k], At[m][k], acc[ai][bj][m][n], 0, 0, 0); __builtin_amdgcn_s_setprio(0); } while (0)
; #define PG8_WAIT_V(n) asm volatile("s_waitcnt vmcnt(" #n ")" ::: "memory")
; #define PG8_WAIT_L(n) asm volatile("s_waitcnt lgkmcnt(" #n ")" ::: "memory")
; #define PG8_BAR __builtin_amdgcn_s_barrier()
; #define PG8_SCHED __builtin_amdgcn_sched_barrier(0)
; template <class Epi, class Sched, bool ALIGN_EPI = false, bool SP2 = false>
; __device__ __forceinline__ void gemm_phase(PG8_LAS unsigned char* lds, const Gemm g, const Sched& S, const Epi& E) {
;     ...
;         for (int t = 0; t < nt; t += 2) {
;     ...
;             PG8_LDB(B0, 1, 0); PG8_LDB(B1, 1, 1); PG8_SCHED; PG8_LDA(At, 1, 0); PG8_STAGE(PG8_SA(0, 1), a2 + hstep, voffA);
;             PG8_WAIT_V(8); PG8_WAIT_L(0); PG8_BAR; PG8_MMA(0, 0, At, B0); PG8_MMA(0, 1, At, B1); PG8_BAR; PG8_SCHED;
;             PG8_LDA(At, 1, 1); PG8_STAGE(PG8_SB(1, 0), b3, voffB); PG8_STAGE(PG8_SB(1, 1), b3 + hstep, voffB); PG8_STAGE(PG8_SA(1, 0), a3, voffA);
;             PG8_WAIT_V(8); PG8_WAIT_L(0); PG8_BAR; PG8_MMA(1, 0, At, B0); PG8_MMA(1, 1, At, B1); PG8_BAR; PG8_SCHED;
	s_setprio 0
	s_add_i32 s60, 0, 0x18000
	s_add_i32 s61, 0, 0x1c000
	ds_read_b128 v[140:143], v248 offset:32768
	ds_read_b128 v[152:155], v248 offset:33792
	ds_read_b128 v[156:159], v248 offset:34816
	ds_read_b128 v[160:163], v248 offset:35840
	ds_read_b128 v[164:167], v248 offset:49152
	ds_read_b128 v[168:171], v248 offset:50176
	ds_read_b128 v[172:175], v248 offset:51200
	ds_read_b128 v[176:179], v248 offset:52224
	s_add_u32 s52, s52, 0x80000
	s_addc_u32 s53, s53, 0
	s_mov_b32 m0, s7
	ds_read_b128 v[180:183], v151 offset:32768
	ds_read_b128 v[184:187], v151 offset:33792
	ds_read_b128 v[188:191], v151 offset:34816
	ds_read_b128 v[192:195], v151 offset:35840
	ds_read_b128 v[196:199], v151 offset:36864
	ds_read_b128 v[200:203], v151 offset:37888
	ds_read_b128 v[204:207], v151 offset:38912
	ds_read_b128 v[208:211], v151 offset:39936
	global_load_lds_dwordx4 v130, s[52:53]
	s_mov_b32 m0, s17
	s_nop 0
	global_load_lds_dwordx4 v132, s[52:53]
	s_waitcnt vmcnt(8)
	s_waitcnt lgkmcnt(0)
	s_setprio 1
	s_barrier
	v_mfma_f32_16x16x32_bf16 v[126:129], v[140:143], v[180:183], v[126:129]
	v_mfma_f32_16x16x32_bf16 v[122:125], v[156:159], v[180:183], v[122:125]
	v_mfma_f32_16x16x32_bf16 v[110:113], v[140:143], v[188:191], v[110:113]
	v_mfma_f32_16x16x32_bf16 v[106:109], v[156:159], v[188:191], v[106:109]
	v_mfma_f32_16x16x32_bf16 v[94:97], v[140:143], v[196:199], v[94:97]
	v_mfma_f32_16x16x32_bf16 v[90:93], v[156:159], v[196:199], v[90:93]
	v_mfma_f32_16x16x32_bf16 v[78:81], v[140:143], v[204:207], v[78:81]
	v_mfma_f32_16x16x32_bf16 v[74:77], v[156:159], v[204:207], v[74:77]
	v_mfma_f32_16x16x32_bf16 v[126:129], v[152:155], v[184:187], v[126:129]
	v_mfma_f32_16x16x32_bf16 v[122:125], v[160:163], v[184:187], v[122:125]
	v_mfma_f32_16x16x32_bf16 v[110:113], v[152:155], v[192:195], v[110:113]
	v_mfma_f32_16x16x32_bf16 v[106:109], v[160:163], v[192:195], v[106:109]
	v_mfma_f32_16x16x32_bf16 v[94:97], v[152:155], v[200:203], v[94:97]
	v_mfma_f32_16x16x32_bf16 v[90:93], v[160:163], v[200:203], v[90:93]
	v_mfma_f32_16x16x32_bf16 v[78:81], v[152:155], v[208:211], v[78:81]
	v_mfma_f32_16x16x32_bf16 v[74:77], v[160:163], v[208:211], v[74:77]
	v_mfma_f32_16x16x32_bf16 v[118:121], v[164:167], v[180:183], v[118:121]
	v_mfma_f32_16x16x32_bf16 v[114:117], v[172:175], v[180:183], v[114:117]
	v_mfma_f32_16x16x32_bf16 v[102:105], v[164:167], v[188:191], v[102:105]
	v_mfma_f32_16x16x32_bf16 v[98:101], v[172:175], v[188:191], v[98:101]
	v_mfma_f32_16x16x32_bf16 v[86:89], v[164:167], v[196:199], v[86:89]
	v_mfma_f32_16x16x32_bf16 v[82:85], v[172:175], v[196:199], v[82:85]
	v_mfma_f32_16x16x32_bf16 v[70:73], v[164:167], v[204:207], v[70:73]
	v_mfma_f32_16x16x32_bf16 v[66:69], v[172:175], v[204:207], v[66:69]
	v_mfma_f32_16x16x32_bf16 v[118:121], v[168:171], v[184:187], v[118:121]
	v_mfma_f32_16x16x32_bf16 v[114:117], v[176:179], v[184:187], v[114:117]
	v_mfma_f32_16x16x32_bf16 v[102:105], v[168:171], v[192:195], v[102:105]
	v_mfma_f32_16x16x32_bf16 v[98:101], v[176:179], v[192:195], v[98:101]
	v_mfma_f32_16x16x32_bf16 v[86:89], v[168:171], v[200:203], v[86:89]
	v_mfma_f32_16x16x32_bf16 v[82:85], v[176:179], v[200:203], v[82:85]
	v_mfma_f32_16x16x32_bf16 v[70:73], v[168:171], v[208:211], v[70:73]
	v_mfma_f32_16x16x32_bf16 v[66:69], v[176:179], v[208:211], v[66:69]
	s_barrier
	s_setprio 0
	s_add_i32 s52, s60, s4
	s_mov_b32 m0, s52
	ds_read_b128 v[180:183], v151 offset:49152
	ds_read_b128 v[184:187], v151 offset:50176
	ds_read_b128 v[188:191], v151 offset:51200
	ds_read_b128 v[192:195], v151 offset:52224
	ds_read_b128 v[196:199], v151 offset:53248
	ds_read_b128 v[200:203], v151 offset:54272
	ds_read_b128 v[204:207], v151 offset:55296
	ds_read_b128 v[208:211], v151 offset:56320
	global_load_lds_dwordx4 v0, s[100:101]
	s_add_i32 m0, s52, 0x2000
	s_add_i32 s52, s61, s4
	global_load_lds_dwordx4 v134, s[100:101]
	s_add_u32 s10, s10, 0x80080
	s_addc_u32 s11, s11, 0
	s_mov_b32 m0, s52
	s_nop 0
	global_load_lds_dwordx4 v0, s[10:11]
	s_add_i32 m0, s52, 0x2000
	s_nop 0
	global_load_lds_dwordx4 v134, s[10:11]
	s_mov_b32 m0, s30
	s_nop 0
	global_load_lds_dwordx4 v130, s[98:99]
	s_mov_b32 m0, s47
	s_nop 0
	global_load_lds_dwordx4 v132, s[98:99]
	s_waitcnt vmcnt(8)
	s_waitcnt lgkmcnt(0)
	s_setprio 1
	s_barrier
	v_mfma_f32_16x16x32_bf16 v[62:65], v[140:143], v[180:183], v[62:65]
	v_mfma_f32_16x16x32_bf16 v[58:61], v[156:159], v[180:183], v[58:61]
	v_mfma_f32_16x16x32_bf16 v[46:49], v[140:143], v[188:191], v[46:49]
	v_mfma_f32_16x16x32_bf16 v[42:45], v[156:159], v[188:191], v[42:45]
	v_mfma_f32_16x16x32_bf16 v[30:33], v[140:143], v[196:199], v[30:33]
	v_mfma_f32_16x16x32_bf16 v[26:29], v[156:159], v[196:199], v[26:29]
	v_mfma_f32_16x16x32_bf16 v[14:17], v[140:143], v[204:207], v[14:17]
	v_mfma_f32_16x16x32_bf16 v[10:13], v[156:159], v[204:207], v[10:13]
	v_mfma_f32_16x16x32_bf16 v[62:65], v[152:155], v[184:187], v[62:65]
	v_mfma_f32_16x16x32_bf16 v[58:61], v[160:163], v[184:187], v[58:61]
	v_mfma_f32_16x16x32_bf16 v[46:49], v[152:155], v[192:195], v[46:49]
	v_mfma_f32_16x16x32_bf16 v[42:45], v[160:163], v[192:195], v[42:45]
	v_mfma_f32_16x16x32_bf16 v[30:33], v[152:155], v[200:203], v[30:33]
	v_mfma_f32_16x16x32_bf16 v[26:29], v[160:163], v[200:203], v[26:29]
	v_mfma_f32_16x16x32_bf16 v[14:17], v[152:155], v[208:211], v[14:17]
	v_mfma_f32_16x16x32_bf16 v[10:13], v[160:163], v[208:211], v[10:13]
	v_mfma_f32_16x16x32_bf16 v[54:57], v[164:167], v[180:183], v[54:57]
	v_mfma_f32_16x16x32_bf16 v[50:53], v[172:175], v[180:183], v[50:53]
	v_mfma_f32_16x16x32_bf16 v[38:41], v[164:167], v[188:191], v[38:41]
	v_mfma_f32_16x16x32_bf16 v[34:37], v[172:175], v[188:191], v[34:37]
	v_mfma_f32_16x16x32_bf16 v[22:25], v[164:167], v[196:199], v[22:25]
	v_mfma_f32_16x16x32_bf16 v[18:21], v[172:175], v[196:199], v[18:21]
	v_mfma_f32_16x16x32_bf16 v[6:9], v[164:167], v[204:207], v[6:9]
	v_mfma_f32_16x16x32_bf16 v[2:5], v[172:175], v[204:207], v[2:5]
	v_mfma_f32_16x16x32_bf16 v[54:57], v[168:171], v[184:187], v[54:57]
	v_mfma_f32_16x16x32_bf16 v[50:53], v[176:179], v[184:187], v[50:53]
	v_mfma_f32_16x16x32_bf16 v[38:41], v[168:171], v[192:195], v[38:41]
	v_mfma_f32_16x16x32_bf16 v[34:37], v[176:179], v[192:195], v[34:37]
	v_mfma_f32_16x16x32_bf16 v[22:25], v[168:171], v[200:203], v[22:25]
	v_mfma_f32_16x16x32_bf16 v[18:21], v[176:179], v[200:203], v[18:21]
	v_mfma_f32_16x16x32_bf16 v[6:9], v[168:171], v[208:211], v[6:9]
	v_mfma_f32_16x16x32_bf16 v[2:5], v[176:179], v[208:211], v[2:5]
	s_barrier
	s_setprio 0
	s_add_i32 s59, s59, 2
	s_add_u32 s50, s50, 0x100
	s_addc_u32 s51, s51, 0
	s_add_u32 s57, s57, 0x100
	s_addc_u32 s58, s58, 0
	s_cmp_gt_u32 s59, 29
	s_cbranch_scc0 .LBB0_559
	s_and_b64 vcc, exec, s[14:15]
	s_cbranch_vccz .LBB0_562
	s_barrier
